# attention loops: merged canonicalizing v_max triples and dropped 0+x adds (replaced by s_nop to keep hazard distances)
# baseline (speedup 1.0000x reference)
.LBB0_869:
	s_cmpk_gt_i32 s63, 0x1ff
	s_mov_b64 s[4:5], -1
	s_cbranch_scc0 .LBB0_931
	s_cmpk_gt_u32 s63, 0x43f
	s_cbranch_scc0 .LBB0_905
	s_add_i32 s12, s63, 0xfffffbc0
	s_cmp_ge_i32 s12, s71
	s_cbranch_scc0 .LBB0_898
	s_sub_i32 s13, s12, s71
	s_cmp_ge_i32 s13, s95
	s_cbranch_scc0 .LBB0_885
	s_sub_i32 s4, s13, s95
	s_lshr_b32 s17, s4, 3
	s_and_b32 s18, s63, 7
	s_mul_i32 s5, s17, 0x1200000
	s_mul_hi_u32 s4, s17, 0x1200000
	s_add_u32 s6, s82, s5
	s_addc_u32 s7, s83, s4
	s_lshl_b32 s4, s18, 7
	s_add_u32 s10, s6, s4
	s_addc_u32 s11, s7, 0
	s_lshl_b32 s4, s63, 5
	s_and_b32 s8, s4, 0x80
	s_load_dwordx2 s[4:5], s[0:1], 0x58
	s_add_u32 s8, s6, s8
	s_addc_u32 s9, s7, 0
	s_or_b32 s40, s18, s70
	s_lshl_b64 s[6:7], s[40:41], 2
	s_waitcnt lgkmcnt(0)
	s_add_u32 s4, s4, s6
	s_addc_u32 s5, s5, s7
	v_mov_b32_e32 v36, v188
	global_load_dword v193, v1, s[4:5]
	v_mov_b32_e32 v6, v1
	v_readfirstlane_b32 s19, v36
	s_ashr_i32 s16, s19, 6
	s_lshl_b32 s6, s16, 5
	s_ashr_i32 s7, s6, 31
	v_and_b32_e32 v189, 63, v36
	s_lshl_b64 s[4:5], s[6:7], 13
	s_add_u32 s10, s10, s4
	v_lshlrev_b32_e32 v0, 13, v189
	s_addc_u32 s11, s11, s5
	v_lshl_add_u64 v[2:3], s[8:9], 0, v[0:1]
	s_lshl_b32 s5, s16, 4
	v_bfe_u32 v0, v36, 2, 4
	v_and_or_b32 v0, s5, 48, v0
	v_lshlrev_b32_e32 v0, 13, v0
	s_ashr_i32 s5, s19, 3
	v_lshl_add_u64 v[4:5], s[8:9], 0, v[0:1]
	s_and_b32 s8, s5, 0xffffffe0
	v_lshlrev_b32_e32 v190, 3, v36
	s_lshl_b32 s26, s16, 3
	s_ashr_i32 s9, s8, 31
	v_and_b32_e32 v194, 24, v190
	s_and_b32 s4, s19, 0x3fffffc0
	s_ashr_i32 s27, s26, 31
	v_lshl_add_u64 v[4:5], s[8:9], 1, v[4:5]
	v_lshlrev_b32_e32 v0, 1, v194
	s_lshl_b32 s5, s16, 10
	v_lshl_add_u64 v[38:39], v[4:5], 0, v[0:1]
	s_mov_b64 s[8:9], 0xb00
	s_cmp_lg_u32 0, -1
	v_lshl_add_u64 v[34:35], s[26:27], 1, v[2:3]
	s_mov_b64 s[26:27], 0xa00
	v_lshl_add_u64 v[186:187], v[38:39], 0, s[8:9]
	s_cselect_b32 s8, 0, 0
	v_and_b32_e32 v191, 31, v36
	v_lshl_add_u64 v[2:3], v[34:35], 0, s[26:27]
	s_add_i32 s8, s8, s5
	s_mov_b32 s5, m0
	s_mov_b32 m0, s8
	s_nop 0
	global_load_lds_dwordx4 v[2:3], off
	s_mov_b32 m0, s5
	v_bfe_u32 v192, v36, 5, 1
	s_add_i32 s19, s8, 0x6000
	s_mov_b32 s5, m0
	s_mov_b32 m0, s19
	s_nop 0
	global_load_lds_dwordx4 v[186:187], off
	s_mov_b32 m0, s5
	s_mov_b64 s[26:27], 0x80a00
	v_lshlrev_b32_e32 v0, 13, v191
	v_lshl_add_u64 v[2:3], v[34:35], 0, s[26:27]
	s_add_i32 s5, s8, 0x2000
	s_mov_b32 s9, m0
	s_mov_b32 m0, s5
	s_nop 0
	global_load_lds_dwordx4 v[2:3], off
	s_mov_b32 m0, s9
	v_lshl_or_b32 v0, v192, 4, v0
	global_load_dwordx4 v[146:149], v0, s[10:11] offset:1536
	global_load_dwordx4 v[142:145], v0, s[10:11] offset:1568
	global_load_dwordx4 v[126:129], v0, s[10:11] offset:1600
	global_load_dwordx4 v[114:117], v0, s[10:11] offset:1632
	v_mov_b32_e32 v2, v1
	v_mov_b32_e32 v3, v1
	v_mov_b32_e32 v4, v1
	v_mov_b32_e32 v5, v1
	v_mov_b32_e32 v7, v1
	v_mov_b32_e32 v8, v1
	v_mov_b32_e32 v9, v1
	v_mov_b32_e32 v10, v1
	v_mov_b32_e32 v11, v1
	v_mov_b32_e32 v12, v1
	v_mov_b32_e32 v13, v1
	v_mov_b32_e32 v14, v1
	v_mov_b32_e32 v15, v1
	v_lshlrev_b32_e32 v0, 4, v191
	v_lshl_add_u32 v16, v192, 10, 0
	v_add_u32_e32 v200, v16, v0
	v_mov_b32_e32 v0, v1
	v_mov_b64_e32 v[16:17], v[14:15]
	s_mov_b64 s[10:11], 0x100a00
	v_mov_b64_e32 v[14:15], v[12:13]
	v_mov_b64_e32 v[12:13], v[10:11]
	v_mov_b64_e32 v[10:11], v[8:9]
	v_mov_b64_e32 v[8:9], v[6:7]
	v_mov_b64_e32 v[6:7], v[4:5]
	v_mov_b64_e32 v[4:5], v[2:3]
	v_mov_b64_e32 v[2:3], v[0:1]
	v_lshl_add_u64 v[18:19], v[34:35], 0, s[10:11]
	s_add_i32 s5, s8, 0x4000
	s_mov_b32 s9, m0
	s_mov_b32 m0, s5
	s_nop 0
	global_load_lds_dwordx4 v[18:19], off
	s_mov_b32 m0, s9
	s_waitcnt vmcnt(3) lgkmcnt(0)
	s_barrier
	ds_read_b128 v[40:43], v200
	ds_read_b128 v[44:47], v200 offset:512
	v_lshlrev_b32_e32 v0, 1, v36
	v_lshlrev_b32_e32 v36, 4, v36
	v_and_b32_e32 v195, 32, v0
	v_and_b32_e32 v0, 0xc0, v36
	v_lshl_or_b32 v196, v192, 8, v0
	s_lshl_b32 s4, s4, 2
	s_waitcnt vmcnt(3) lgkmcnt(1)
	v_mfma_f32_32x32x16_bf16 v[18:33], v[40:43], v[146:149], v[2:17]
	v_add3_u32 v36, 0, v195, v194
	s_add_i32 s25, s4, 0
	s_mov_b64 s[4:5], 0x180a00
	v_add_u32_e32 v199, v36, v196
	v_lshl_add_u32 v197, v191, 2, s25
	s_waitcnt lgkmcnt(0)
	v_mfma_f32_32x32x16_bf16 v[2:17], v[44:47], v[146:149], v[2:17]
	ds_read_b128 v[40:43], v200 offset:2048
	ds_read_b128 v[44:47], v200 offset:2560
	s_waitcnt vmcnt(2) lgkmcnt(1)
	v_mfma_f32_32x32x16_bf16 v[18:33], v[40:43], v[142:145], v[18:33]
	s_waitcnt lgkmcnt(0)
	v_mfma_f32_32x32x16_bf16 v[2:17], v[44:47], v[142:145], v[2:17]
	ds_read_b128 v[40:43], v200 offset:4096
	ds_read_b128 v[44:47], v200 offset:4608
	s_waitcnt vmcnt(1) lgkmcnt(1)
	v_mfma_f32_32x32x16_bf16 v[18:33], v[40:43], v[126:129], v[18:33]
	s_waitcnt lgkmcnt(0)
	v_mfma_f32_32x32x16_bf16 v[2:17], v[44:47], v[126:129], v[2:17]
	ds_read_b128 v[40:43], v200 offset:6144
	ds_read_b128 v[44:47], v200 offset:6656
	s_waitcnt vmcnt(0) lgkmcnt(1)
	v_mfma_f32_32x32x16_bf16 v[18:33], v[40:43], v[114:117], v[18:33]
	s_waitcnt lgkmcnt(0)
	v_mfma_f32_32x32x16_bf16 v[2:17], v[44:47], v[114:117], v[2:17]
	s_nop 15
	s_nop 7
	s_nop 0
	v_max3_f32 v0, v18, v19, v2
	v_max3_f32 v37, v20, v21, v3
	s_nop 0
	v_max3_f32 v0, v0, v4, v5
	v_max3_f32 v37, v37, v24, v25
	s_nop 0
	v_max3_f32 v0, v0, v22, v23
	v_max3_f32 v37, v37, v8, v9
	s_nop 0
	v_max3_f32 v0, v0, v6, v7
	v_max3_f32 v37, v37, v28, v29
	s_nop 0
	v_max3_f32 v0, v0, v26, v27
	v_max3_f32 v37, v37, v12, v13
	s_nop 0
	v_max3_f32 v0, v0, v10, v11
	v_max3_f32 v37, v37, v32, v33
	s_nop 0
	v_max3_f32 v0, v0, v30, v31
	v_max3_f32 v37, v37, v16, v17
	s_nop 0
	v_max3_f32 v0, v0, v14, v15
	s_nop 0
	v_max_f32_e32 v0, v0, v37
	s_nop 0
	v_mov_b32_e32 v37, v0
	s_nop 1
	v_permlane32_swap_b32_e32 v0, v37
	v_max_f32_e32 v37, v0, v37
	s_nop 0
	v_add_f32_e32 v0, v1, v37
	v_sub_f32_e32 v40, v2, v37
	v_sub_f32_e32 v18, v18, v37
	v_sub_f32_e32 v19, v19, v37
	v_sub_f32_e32 v41, v3, v37
	v_sub_f32_e32 v20, v20, v37
	s_nop 0
	v_xor_b32_e32 v2, 0x80000000, v0
	v_sub_f32_e32 v42, v4, v37
	v_sub_f32_e32 v21, v21, v37
	v_sub_f32_e32 v43, v5, v37
	v_sub_f32_e32 v22, v22, v37
	v_sub_f32_e32 v44, v6, v37
	v_sub_f32_e32 v23, v23, v37
	v_sub_f32_e32 v45, v7, v37
	v_sub_f32_e32 v24, v24, v37
	v_sub_f32_e32 v46, v8, v37
	v_sub_f32_e32 v25, v25, v37
	v_sub_f32_e32 v47, v9, v37
	v_sub_f32_e32 v26, v26, v37
	v_sub_f32_e32 v48, v10, v37
	v_sub_f32_e32 v27, v27, v37
	v_sub_f32_e32 v49, v11, v37
	v_sub_f32_e32 v28, v28, v37
	v_sub_f32_e32 v50, v12, v37
	v_sub_f32_e32 v29, v29, v37
	v_sub_f32_e32 v51, v13, v37
	v_sub_f32_e32 v30, v30, v37
	v_sub_f32_e32 v52, v14, v37
	v_sub_f32_e32 v31, v31, v37
	v_sub_f32_e32 v53, v15, v37
	v_sub_f32_e32 v32, v32, v37
	v_sub_f32_e32 v54, v16, v37
	v_sub_f32_e32 v33, v33, v37
	v_sub_f32_e32 v37, v17, v37
	v_mov_b32_e32 v3, v2
	v_mov_b32_e32 v4, v2
	v_mov_b32_e32 v5, v2
	v_mov_b32_e32 v6, v2
	v_mov_b32_e32 v7, v2
	v_mov_b32_e32 v8, v2
	v_mov_b32_e32 v9, v2
	v_mov_b32_e32 v10, v2
	v_mov_b32_e32 v11, v2
	v_mov_b32_e32 v12, v2
	v_mov_b32_e32 v13, v2
	v_mov_b32_e32 v14, v2
	v_mov_b32_e32 v15, v2
	v_mov_b32_e32 v16, v2
	v_mov_b32_e32 v17, v2
	s_waitcnt vmcnt(0) lgkmcnt(0)
	s_barrier
	v_exp_f32_e32 v36, v18
	v_exp_f32_e32 v55, v19
	v_lshl_add_u64 v[18:19], v[34:35], 0, s[4:5]
	s_mov_b32 s4, m0
	s_mov_b32 m0, s8
	s_nop 0
	global_load_lds_dwordx4 v[18:19], off
	s_mov_b32 m0, s4
	s_mov_b64 s[4:5], 0x80b00
	v_lshl_add_u64 v[18:19], v[38:39], 0, s[4:5]
	s_add_i32 s4, s8, 0x8000
	s_mov_b32 s5, m0
	s_mov_b32 m0, s4
	s_nop 0
	global_load_lds_dwordx4 v[18:19], off
	s_mov_b32 m0, s5
	v_exp_f32_e32 v58, v22
	v_exp_f32_e32 v59, v23
	v_exp_f32_e32 v60, v24
	v_exp_f32_e32 v61, v25
	v_exp_f32_e32 v62, v26
	v_exp_f32_e32 v63, v27
	v_exp_f32_e32 v64, v28
	v_exp_f32_e32 v65, v29
	v_exp_f32_e32 v94, v30
	v_exp_f32_e32 v95, v31
	v_exp_f32_e32 v96, v32
	v_exp_f32_e32 v97, v33
	v_exp_f32_e32 v134, v40
	v_exp_f32_e32 v135, v41
	v_exp_f32_e32 v136, v42
	v_exp_f32_e32 v137, v43
	v_exp_f32_e32 v138, v44
	v_exp_f32_e32 v139, v45
	v_exp_f32_e32 v140, v46
	v_exp_f32_e32 v141, v47
	ds_read_b128 v[22:25], v200 offset:8192
	ds_read_b128 v[26:29], v200 offset:8704
	ds_read_b128 v[30:33], v200 offset:10240
	ds_read_b128 v[40:43], v200 offset:10752
	ds_read_b128 v[44:47], v200 offset:12288
	ds_read_b128 v[82:85], v200 offset:12800
	ds_read_b128 v[86:89], v200 offset:14336
	ds_read_b128 v[90:93], v200 offset:14848
	v_exp_f32_e32 v56, v20
	v_exp_f32_e32 v57, v21
	s_waitcnt vmcnt(2) lgkmcnt(0)
	s_barrier
	v_cmp_gt_u32_e64 s[4:5], 32, v189
	v_exp_f32_e32 v48, v48
	v_exp_f32_e32 v49, v49
	v_exp_f32_e32 v150, v50
	v_exp_f32_e32 v151, v51
	v_exp_f32_e32 v152, v52
	v_exp_f32_e32 v153, v53
	v_exp_f32_e32 v154, v54
	v_exp_f32_e32 v155, v37
	ds_read_b64_tr_b16 v[18:19], v199 offset:24576
	ds_read_b64_tr_b16 v[20:21], v199 offset:25088
	s_waitcnt lgkmcnt(9)
	v_mfma_f32_32x32x16_bf16 v[98:113], v[22:25], v[146:149], v[2:17]
	v_add_f32_e32 v34, v36, v55
	v_add_f32_e32 v34, v34, v56
	v_add_f32_e32 v34, v34, v57
	v_add_f32_e32 v34, v34, v58
	v_add_f32_e32 v50, v34, v59
	v_cvt_pk_bf16_f32 v122, v36, v55
	v_cvt_pk_bf16_f32 v123, v56, v57
	ds_read_b64_tr_b16 v[34:35], v199 offset:28672
	ds_read_b64_tr_b16 v[36:37], v199 offset:29184
	s_waitcnt lgkmcnt(10)
	v_mfma_f32_32x32x16_bf16 v[66:81], v[26:29], v[146:149], v[2:17]
	v_add_f32_e32 v22, v60, v50
	v_add_f32_e32 v22, v61, v22
	v_add_f32_e32 v22, v62, v22
	v_add_f32_e32 v22, v63, v22
	v_cvt_pk_bf16_f32 v124, v58, v59
	v_cvt_pk_bf16_f32 v125, v60, v61
	ds_read_b64_tr_b16 v[50:51], v199 offset:25600
	ds_read_b64_tr_b16 v[52:53], v199 offset:26112
	s_waitcnt lgkmcnt(11)
	v_mfma_f32_32x32x16_bf16 v[98:113], v[30:33], v[142:145], v[98:113]
	v_add_f32_e32 v22, v64, v22
	v_add_f32_e32 v22, v65, v22
	v_add_f32_e32 v22, v94, v22
	v_add_f32_e32 v22, v95, v22
	v_cvt_pk_bf16_f32 v118, v62, v63
	v_cvt_pk_bf16_f32 v119, v64, v65
	ds_read_b64_tr_b16 v[54:55], v199 offset:29696
	ds_read_b64_tr_b16 v[56:57], v199 offset:30208
	s_waitcnt lgkmcnt(12)
	v_mfma_f32_32x32x16_bf16 v[66:81], v[40:43], v[142:145], v[66:81]
	v_add_f32_e32 v22, v96, v22
	v_add_f32_e32 v22, v97, v22
	v_add_f32_e32 v22, v134, v22
	v_add_f32_e32 v22, v135, v22
	v_cvt_pk_bf16_f32 v120, v94, v95
	v_cvt_pk_bf16_f32 v121, v96, v97
	ds_read_b64_tr_b16 v[58:59], v199 offset:26624
	ds_read_b64_tr_b16 v[60:61], v199 offset:27136
	s_waitcnt lgkmcnt(13)
	v_mfma_f32_32x32x16_bf16 v[98:113], v[44:47], v[126:129], v[98:113]
	v_add_f32_e32 v22, v136, v22
	v_add_f32_e32 v22, v137, v22
	v_add_f32_e32 v22, v138, v22
	v_add_f32_e32 v22, v139, v22
	v_cvt_pk_bf16_f32 v134, v134, v135
	v_cvt_pk_bf16_f32 v135, v136, v137
	ds_read_b64_tr_b16 v[62:63], v199 offset:30720
	ds_read_b64_tr_b16 v[64:65], v199 offset:31232
	s_waitcnt lgkmcnt(14)
	v_mfma_f32_32x32x16_bf16 v[66:81], v[82:85], v[126:129], v[66:81]
	v_add_f32_e32 v22, v140, v22
	v_add_f32_e32 v22, v141, v22
	v_add_f32_e32 v22, v48, v22
	v_add_f32_e32 v22, v49, v22
	v_cvt_pk_bf16_f32 v136, v138, v139
	v_cvt_pk_bf16_f32 v137, v140, v141
	ds_read_b64_tr_b16 v[82:83], v199 offset:27648
	ds_read_b64_tr_b16 v[84:85], v199 offset:28160
	s_waitcnt lgkmcnt(14)
	v_mfma_f32_32x32x16_bf16 v[98:113], v[86:89], v[114:117], v[98:113]
	v_add_f32_e32 v22, v150, v22
	v_add_f32_e32 v22, v151, v22
	v_add_f32_e32 v22, v152, v22
	v_add_f32_e32 v22, v153, v22
	v_cvt_pk_bf16_f32 v138, v48, v49
	v_cvt_pk_bf16_f32 v139, v150, v151
	ds_read_b64_tr_b16 v[86:87], v199 offset:31744
	ds_read_b64_tr_b16 v[88:89], v199 offset:32256
	v_mfma_f32_32x32x16_bf16 v[66:81], v[90:93], v[114:117], v[66:81]
	v_add_f32_e32 v22, v154, v22
	v_add_f32_e32 v22, v155, v22
	s_nop 0
	v_cvt_pk_bf16_f32 v140, v152, v153
	v_cvt_pk_bf16_f32 v141, v154, v155
	s_mov_b64 s[10:11], 0x100b00
	v_add_f32_e32 v201, 0, v22
	v_lshl_add_u64 v[22:23], v[38:39], 0, s[10:11]
	s_add_i32 s8, s8, 0xa000
	s_mov_b32 s9, m0
	s_mov_b32 m0, s8
	s_nop 0
	global_load_lds_dwordx4 v[22:23], off
	s_mov_b32 m0, s9
	v_max_f32_e32 v22, v99, v98
	s_nop 1
	v_max3_f32 v23, v100, v101, v67
	v_max3_f32 v22, v22, v66, v68
	v_max3_f32 v22, v22, v69, v102
	v_max3_f32 v23, v23, v104, v105
	v_max3_f32 v22, v22, v103, v70
	v_max3_f32 v23, v23, v72, v73
	v_max3_f32 v22, v22, v71, v106
	v_max3_f32 v23, v23, v108, v109
	v_max3_f32 v22, v22, v107, v74
	v_max3_f32 v23, v23, v76, v77
	v_max3_f32 v22, v22, v75, v110
	v_max3_f32 v23, v23, v112, v113
	v_max3_f32 v22, v22, v111, v78
	v_max3_f32 v23, v23, v80, v81
	v_max3_f32 v22, v22, v79, v23
	v_mov_b32_e32 v23, v22
	s_nop 1
	v_permlane32_swap_b32_e32 v22, v23
	s_nop 1
	v_max_f32_e32 v22, v22, v23
	v_cmp_lt_f32_e32 vcc, s22, v22
	s_cmp_lg_u64 vcc, 0
	s_cselect_b64 s[8:9], -1, 0
	s_cbranch_vccnz .LBB0_988

.LBB0_876:
	ds_read_b64_tr_b16 v[154:155], v199 offset:32768
	ds_read_b64_tr_b16 v[156:157], v199 offset:33280
	s_waitcnt lgkmcnt(9)
	v_mfma_f32_32x32x16_bf16 v[82:97], v[150:153], v[146:149], v[2:17]
	v_add_f32_e32 v50, v98, v99
	v_add_f32_e32 v50, v100, v50
	v_add_f32_e32 v50, v101, v50
	v_add_f32_e32 v50, v102, v50
	v_add_f32_e32 v50, v103, v50
	v_cvt_pk_bf16_f32 v122, v98, v99
	v_cvt_pk_bf16_f32 v123, v100, v101
	ds_read_b64_tr_b16 v[150:151], v199 offset:36864
	ds_read_b64_tr_b16 v[152:153], v199 offset:37376
	v_add_f32_e32 v50, v104, v50
	v_add_f32_e32 v50, v105, v50
	v_add_f32_e32 v50, v106, v50
	v_add_f32_e32 v118, v107, v50
	s_waitcnt lgkmcnt(10)
	v_mfma_f32_32x32x16_bf16 v[50:65], v[178:181], v[146:149], v[2:17]
	v_cvt_pk_bf16_f32 v124, v102, v103
	v_cvt_pk_bf16_f32 v125, v104, v105
	ds_read_b64_tr_b16 v[98:99], v199 offset:33792
	ds_read_b64_tr_b16 v[100:101], v199 offset:34304
	s_waitcnt lgkmcnt(11)
	v_mfma_f32_32x32x16_bf16 v[82:97], v[182:185], v[142:145], v[82:97]
	v_add_f32_e32 v102, v108, v118
	v_add_f32_e32 v102, v109, v102
	v_add_f32_e32 v102, v110, v102
	v_add_f32_e32 v134, v111, v102
	v_cvt_pk_bf16_f32 v118, v106, v107
	v_cvt_pk_bf16_f32 v119, v108, v109
	ds_read_b64_tr_b16 v[102:103], v199 offset:37888
	ds_read_b64_tr_b16 v[104:105], v199 offset:38400
	s_waitcnt lgkmcnt(12)
	v_mfma_f32_32x32x16_bf16 v[50:65], v[174:177], v[142:145], v[50:65]
	v_add_f32_e32 v106, v112, v134
	v_add_f32_e32 v106, v113, v106
	v_add_f32_e32 v106, v66, v106
	v_add_f32_e32 v134, v67, v106
	v_cvt_pk_bf16_f32 v120, v110, v111
	v_cvt_pk_bf16_f32 v121, v112, v113
	ds_read_b64_tr_b16 v[106:107], v199 offset:34816
	ds_read_b64_tr_b16 v[108:109], v199 offset:35328
	s_waitcnt lgkmcnt(13)
	v_mfma_f32_32x32x16_bf16 v[82:97], v[170:173], v[126:129], v[82:97]
	v_add_f32_e32 v110, v68, v134
	v_add_f32_e32 v110, v69, v110
	v_add_f32_e32 v110, v70, v110
	v_add_f32_e32 v110, v71, v110
	v_cvt_pk_bf16_f32 v134, v66, v67
	v_cvt_pk_bf16_f32 v135, v68, v69
	ds_read_b64_tr_b16 v[66:67], v199 offset:38912
	ds_read_b64_tr_b16 v[68:69], v199 offset:39424
	s_waitcnt lgkmcnt(14)
	v_mfma_f32_32x32x16_bf16 v[50:65], v[166:169], v[126:129], v[50:65]
	v_add_f32_e32 v110, v72, v110
	v_add_f32_e32 v110, v73, v110
	v_add_f32_e32 v110, v74, v110
	v_add_f32_e32 v110, v75, v110
	v_cvt_pk_bf16_f32 v136, v70, v71
	v_cvt_pk_bf16_f32 v137, v72, v73
	ds_read_b64_tr_b16 v[70:71], v199 offset:35840
	ds_read_b64_tr_b16 v[72:73], v199 offset:36352
	s_waitcnt lgkmcnt(14)
	v_mfma_f32_32x32x16_bf16 v[82:97], v[162:165], v[114:117], v[82:97]
	v_add_f32_e32 v110, v76, v110
	v_add_f32_e32 v110, v77, v110
	v_add_f32_e32 v110, v78, v110
	v_add_f32_e32 v110, v79, v110
	v_cvt_pk_bf16_f32 v138, v74, v75
	v_cvt_pk_bf16_f32 v139, v76, v77
	ds_read_b64_tr_b16 v[74:75], v199 offset:39936
	ds_read_b64_tr_b16 v[76:77], v199 offset:40448
	v_mfma_f32_32x32x16_bf16 v[50:65], v[158:161], v[114:117], v[50:65]
	v_add_f32_e32 v110, v80, v110
	v_add_f32_e32 v110, v81, v110
	s_nop 0
	v_cvt_pk_bf16_f32 v140, v78, v79
	v_cvt_pk_bf16_f32 v141, v80, v81
	s_mov_b64 s[8:9], 0x180000
	v_lshl_add_u64 v[78:79], v[186:187], 0, s[8:9]
	s_mov_b32 s8, m0
	s_mov_b32 m0, s19
	s_nop 0
	global_load_lds_dwordx4 v[78:79], off
	s_mov_b32 m0, s8
	v_max_f32_e32 v78, v83, v82
	s_nop 3
	v_max3_f32 v79, v84, v85, v51
	v_max3_f32 v78, v78, v50, v52
	v_max3_f32 v78, v78, v53, v86
	v_max3_f32 v79, v79, v88, v89
	v_max3_f32 v78, v78, v87, v54
	v_max3_f32 v79, v79, v56, v57
	v_max3_f32 v78, v78, v55, v90
	v_max3_f32 v79, v79, v92, v93
	v_max3_f32 v78, v78, v91, v58
	v_max3_f32 v79, v79, v60, v61
	v_max3_f32 v78, v78, v59, v94
	v_max3_f32 v79, v79, v96, v97
	v_max3_f32 v78, v78, v95, v62
	v_max3_f32 v79, v79, v64, v65
	v_max3_f32 v78, v78, v63, v79
	v_mov_b32_e32 v79, v78
	s_nop 1
	v_permlane32_swap_b32_e32 v78, v79
	s_nop 1
	v_max_f32_e32 v78, v78, v79
	v_cmp_lt_f32_e32 vcc, s22, v78
	s_cmp_lg_u64 vcc, 0
	v_add_f32_e32 v174, v201, v110
	s_cselect_b64 s[8:9], -1, 0
	s_cbranch_vccnz .LBB0_991

.LBB0_879:
	ds_read_b64_tr_b16 v[98:99], v199 offset:40960
	ds_read_b64_tr_b16 v[100:101], v199 offset:41472
	v_add_f32_e32 v66, v82, v83
	v_add_f32_e32 v66, v84, v66
	v_add_f32_e32 v66, v85, v66
	v_add_f32_e32 v66, v86, v66
	v_add_f32_e32 v106, v87, v66
	s_waitcnt lgkmcnt(9)
	v_mfma_f32_32x32x16_bf16 v[66:81], v[170:173], v[146:149], v[2:17]
	v_cvt_pk_bf16_f32 v122, v82, v83
	v_cvt_pk_bf16_f32 v123, v84, v85
	ds_read_b64_tr_b16 v[82:83], v199 offset:45056
	ds_read_b64_tr_b16 v[84:85], v199 offset:45568
	s_waitcnt lgkmcnt(10)
	v_mfma_f32_32x32x16_bf16 v[2:17], v[166:169], v[146:149], v[2:17]
	v_add_f32_e32 v106, v88, v106
	v_add_f32_e32 v106, v89, v106
	v_add_f32_e32 v106, v90, v106
	v_add_f32_e32 v106, v91, v106
	v_cvt_pk_bf16_f32 v124, v86, v87
	v_cvt_pk_bf16_f32 v125, v88, v89
	ds_read_b64_tr_b16 v[86:87], v199 offset:41984
	ds_read_b64_tr_b16 v[88:89], v199 offset:42496
	s_waitcnt lgkmcnt(11)
	v_mfma_f32_32x32x16_bf16 v[66:81], v[162:165], v[142:145], v[66:81]
	v_add_f32_e32 v106, v92, v106
	v_add_f32_e32 v106, v93, v106
	v_add_f32_e32 v106, v94, v106
	v_add_f32_e32 v106, v95, v106
	v_cvt_pk_bf16_f32 v118, v90, v91
	v_cvt_pk_bf16_f32 v119, v92, v93
	ds_read_b64_tr_b16 v[90:91], v199 offset:46080
	ds_read_b64_tr_b16 v[92:93], v199 offset:46592
	s_waitcnt lgkmcnt(12)
	v_mfma_f32_32x32x16_bf16 v[2:17], v[158:161], v[142:145], v[2:17]
	v_add_f32_e32 v106, v96, v106
	v_add_f32_e32 v106, v97, v106
	v_add_f32_e32 v106, v50, v106
	v_add_f32_e32 v106, v51, v106
	v_cvt_pk_bf16_f32 v120, v94, v95
	v_cvt_pk_bf16_f32 v121, v96, v97
	ds_read_b64_tr_b16 v[94:95], v199 offset:43008
	ds_read_b64_tr_b16 v[96:97], v199 offset:43520
	s_waitcnt lgkmcnt(13)
	v_mfma_f32_32x32x16_bf16 v[66:81], v[102:105], v[126:129], v[66:81]
	v_add_f32_e32 v102, v52, v106
	v_add_f32_e32 v102, v53, v102
	v_add_f32_e32 v102, v54, v102
	v_add_f32_e32 v106, v55, v102
	v_cvt_pk_bf16_f32 v134, v50, v51
	v_cvt_pk_bf16_f32 v135, v52, v53
	ds_read_b64_tr_b16 v[102:103], v199 offset:47104
	ds_read_b64_tr_b16 v[104:105], v199 offset:47616
	s_waitcnt lgkmcnt(14)
	v_mfma_f32_32x32x16_bf16 v[2:17], v[154:157], v[126:129], v[2:17]
	v_add_f32_e32 v50, v56, v106
	v_add_f32_e32 v50, v57, v50
	v_add_f32_e32 v50, v58, v50
	v_add_f32_e32 v50, v59, v50
	v_cvt_pk_bf16_f32 v136, v54, v55
	v_cvt_pk_bf16_f32 v137, v56, v57
	ds_read_b64_tr_b16 v[106:107], v199 offset:44032
	ds_read_b64_tr_b16 v[108:109], v199 offset:44544
	s_waitcnt lgkmcnt(14)
	v_mfma_f32_32x32x16_bf16 v[66:81], v[150:153], v[114:117], v[66:81]
	v_add_f32_e32 v50, v60, v50
	v_add_f32_e32 v50, v61, v50
	v_add_f32_e32 v50, v62, v50
	v_add_f32_e32 v50, v63, v50
	v_cvt_pk_bf16_f32 v138, v58, v59
	v_cvt_pk_bf16_f32 v139, v60, v61
	ds_read_b64_tr_b16 v[126:127], v199 offset:48128
	ds_read_b64_tr_b16 v[128:129], v199 offset:48640
	v_mfma_f32_32x32x16_bf16 v[2:17], v[110:113], v[114:117], v[2:17]
	v_add_f32_e32 v50, v64, v50
	v_add_f32_e32 v50, v65, v50
	s_nop 0
	v_cvt_pk_bf16_f32 v140, v62, v63
	v_cvt_pk_bf16_f32 v141, v64, v65
	s_nop 0
	v_add_f32_e32 v110, v174, v50
	v_max_f32_e32 v50, v67, v66
	s_nop 3
	v_max3_f32 v51, v68, v69, v3
	v_max3_f32 v50, v50, v2, v4
	v_max3_f32 v50, v50, v5, v70
	v_max3_f32 v51, v51, v72, v73
	v_max3_f32 v50, v50, v71, v6
	v_max3_f32 v51, v51, v8, v9
	v_max3_f32 v50, v50, v7, v74
	v_max3_f32 v51, v51, v76, v77
	v_max3_f32 v50, v50, v75, v10
	v_max3_f32 v51, v51, v12, v13
	v_max3_f32 v50, v50, v11, v78
	v_max3_f32 v51, v51, v80, v81
	v_max3_f32 v50, v50, v79, v14
	v_max3_f32 v51, v51, v16, v17
	v_max3_f32 v50, v50, v15, v51
	v_mov_b32_e32 v51, v50
	s_nop 1
	v_permlane32_swap_b32_e32 v50, v51
	s_nop 1
	v_max_f32_e32 v50, v50, v51
	v_cmp_lt_f32_e32 vcc, s22, v50
	s_cmp_lg_u64 vcc, 0
	s_cselect_b64 s[8:9], -1, 0
	s_cbranch_vccnz .LBB0_994

.LBB0_885:
	s_mov_b32 s8, 0
	s_and_b64 vcc, exec, s[4:5]
	s_cbranch_vccz .LBB0_972
	s_ashr_i32 s16, s13, 3
	s_and_b32 s17, s63, 7
	s_mul_i32 s5, s16, 0x1200000
	s_mul_hi_i32 s4, s16, 0x1200000
	s_add_u32 s5, s82, s5
	s_addc_u32 s4, s83, s4
	s_lshl_b32 s6, s17, 7
	s_add_u32 s10, s5, s6
	s_addc_u32 s11, s4, 0
	s_lshl_b32 s6, s63, 5
	s_and_b32 s6, s6, 0x80
	v_mov_b32_e32 v36, v188
	s_add_u32 s8, s5, s6
	s_addc_u32 s9, s4, 0
	v_readfirstlane_b32 s25, v36
	s_ashr_i32 s13, s25, 6
	s_lshl_b32 s6, s13, 5
	s_ashr_i32 s7, s6, 31
	v_and_b32_e32 v189, 63, v36
	s_lshl_b64 s[4:5], s[6:7], 13
	s_add_u32 s10, s10, s4
	v_lshlrev_b32_e32 v0, 13, v189
	s_addc_u32 s11, s11, s5
	v_lshl_add_u64 v[2:3], s[8:9], 0, v[0:1]
	s_lshl_b32 s5, s13, 4
	v_bfe_u32 v0, v36, 2, 4
	v_and_or_b32 v0, s5, 48, v0
	v_lshlrev_b32_e32 v0, 13, v0
	s_ashr_i32 s5, s25, 3
	v_lshl_add_u64 v[4:5], s[8:9], 0, v[0:1]
	s_and_b32 s8, s5, 0xffffffe0
	v_lshlrev_b32_e32 v190, 3, v36
	s_lshl_b32 s18, s13, 3
	s_ashr_i32 s9, s8, 31
	v_and_b32_e32 v193, 24, v190
	s_and_b32 s4, s25, 0x3fffffc0
	s_ashr_i32 s19, s18, 31
	v_lshl_add_u64 v[4:5], s[8:9], 1, v[4:5]
	v_lshlrev_b32_e32 v0, 1, v193
	s_lshl_b32 s5, s13, 10
	v_lshl_add_u64 v[38:39], v[4:5], 0, v[0:1]
	s_mov_b64 s[8:9], 0x500
	s_cmp_lg_u32 0, -1
	v_lshl_add_u64 v[34:35], s[18:19], 1, v[2:3]
	s_mov_b64 s[18:19], 0x400
	v_lshl_add_u64 v[186:187], v[38:39], 0, s[8:9]
	s_cselect_b32 s8, 0, 0
	v_and_b32_e32 v191, 31, v36
	v_lshl_add_u64 v[2:3], v[34:35], 0, s[18:19]
	s_add_i32 s8, s8, s5
	s_mov_b32 s5, m0
	s_mov_b32 m0, s8
	s_nop 0
	global_load_lds_dwordx4 v[2:3], off
	s_mov_b32 m0, s5
	v_bfe_u32 v192, v36, 5, 1
	s_add_i32 s18, s8, 0x6000
	s_mov_b32 s5, m0
	s_mov_b32 m0, s18
	s_nop 0
	global_load_lds_dwordx4 v[186:187], off
	s_mov_b32 m0, s5
	s_mov_b64 s[26:27], 0x80400
	v_lshlrev_b32_e32 v0, 13, v191
	v_lshl_add_u64 v[2:3], v[34:35], 0, s[26:27]
	s_add_i32 s5, s8, 0x2000
	s_mov_b32 s9, m0
	s_mov_b32 m0, s5
	s_nop 0
	global_load_lds_dwordx4 v[2:3], off
	s_mov_b32 m0, s9
	v_lshl_or_b32 v0, v192, 4, v0
	global_load_dwordx4 v[146:149], v0, s[10:11]
	global_load_dwordx4 v[142:145], v0, s[10:11] offset:32
	global_load_dwordx4 v[118:121], v0, s[10:11] offset:64
	global_load_dwordx4 v[114:117], v0, s[10:11] offset:96
	v_mov_b32_e32 v2, v1
	v_mov_b32_e32 v3, v1
	v_mov_b32_e32 v4, v1
	v_mov_b32_e32 v5, v1
	v_mov_b32_e32 v6, v1
	v_mov_b32_e32 v7, v1
	v_mov_b32_e32 v8, v1
	v_mov_b32_e32 v9, v1
	v_mov_b32_e32 v10, v1
	v_mov_b32_e32 v11, v1
	v_mov_b32_e32 v12, v1
	v_mov_b32_e32 v13, v1
	v_mov_b32_e32 v14, v1
	v_mov_b32_e32 v15, v1
	v_lshlrev_b32_e32 v0, 4, v191
	v_lshl_add_u32 v16, v192, 10, 0
	v_add_u32_e32 v199, v16, v0
	v_mov_b32_e32 v0, v1
	v_mov_b64_e32 v[16:17], v[14:15]
	s_mov_b64 s[10:11], 0x100400
	v_mov_b64_e32 v[14:15], v[12:13]
	v_mov_b64_e32 v[12:13], v[10:11]
	v_mov_b64_e32 v[10:11], v[8:9]
	v_mov_b64_e32 v[8:9], v[6:7]
	v_mov_b64_e32 v[6:7], v[4:5]
	v_mov_b64_e32 v[4:5], v[2:3]
	v_mov_b64_e32 v[2:3], v[0:1]
	v_lshl_add_u64 v[18:19], v[34:35], 0, s[10:11]
	s_add_i32 s5, s8, 0x4000
	s_mov_b32 s9, m0
	s_mov_b32 m0, s5
	s_nop 0
	global_load_lds_dwordx4 v[18:19], off
	s_mov_b32 m0, s9
	s_waitcnt vmcnt(3) lgkmcnt(0)
	s_barrier
	ds_read_b128 v[40:43], v199
	ds_read_b128 v[44:47], v199 offset:512
	s_lshl_b32 s4, s4, 2
	s_add_i32 s19, s4, 0
	s_mov_b64 s[4:5], 0x180400
	v_lshlrev_b32_e32 v0, 1, v36
	v_lshlrev_b32_e32 v36, 4, v36
	v_and_b32_e32 v0, 32, v0
	s_waitcnt vmcnt(3) lgkmcnt(1)
	v_mfma_f32_32x32x16_bf16 v[18:33], v[40:43], v[146:149], v[2:17]
	v_and_b32_e32 v36, 0xc0, v36
	v_lshl_or_b32 v194, v192, 8, v36
	v_add3_u32 v36, 0, v0, v193
	v_add_u32_e32 v198, v36, v194
	v_lshl_add_u32 v195, v191, 2, s19
	s_waitcnt lgkmcnt(0)
	v_mfma_f32_32x32x16_bf16 v[2:17], v[44:47], v[146:149], v[2:17]
	ds_read_b128 v[40:43], v199 offset:2048
	ds_read_b128 v[44:47], v199 offset:2560
	s_waitcnt vmcnt(2) lgkmcnt(1)
	v_mfma_f32_32x32x16_bf16 v[18:33], v[40:43], v[142:145], v[18:33]
	s_waitcnt lgkmcnt(0)
	v_mfma_f32_32x32x16_bf16 v[2:17], v[44:47], v[142:145], v[2:17]
	ds_read_b128 v[40:43], v199 offset:4096
	ds_read_b128 v[44:47], v199 offset:4608
	s_waitcnt vmcnt(1) lgkmcnt(1)
	v_mfma_f32_32x32x16_bf16 v[18:33], v[40:43], v[118:121], v[18:33]
	s_waitcnt lgkmcnt(0)
	v_mfma_f32_32x32x16_bf16 v[2:17], v[44:47], v[118:121], v[2:17]
	ds_read_b128 v[40:43], v199 offset:6144
	ds_read_b128 v[44:47], v199 offset:6656
	s_waitcnt vmcnt(0) lgkmcnt(1)
	v_mfma_f32_32x32x16_bf16 v[18:33], v[40:43], v[114:117], v[18:33]
	s_waitcnt lgkmcnt(0)
	v_mfma_f32_32x32x16_bf16 v[2:17], v[44:47], v[114:117], v[2:17]
	s_nop 15
	s_nop 7
	s_nop 0
	v_max3_f32 v37, v18, v19, v2
	v_max3_f32 v40, v20, v21, v3
	s_nop 0
	v_max3_f32 v37, v37, v4, v5
	v_max3_f32 v40, v40, v24, v25
	s_nop 0
	v_max3_f32 v37, v37, v22, v23
	v_max3_f32 v40, v40, v8, v9
	s_nop 0
	v_max3_f32 v37, v37, v6, v7
	v_max3_f32 v40, v40, v28, v29
	s_nop 0
	v_max3_f32 v37, v37, v26, v27
	v_max3_f32 v40, v40, v12, v13
	s_nop 0
	v_max3_f32 v37, v37, v10, v11
	v_max3_f32 v40, v40, v32, v33
	s_nop 0
	v_max3_f32 v37, v37, v30, v31
	v_max3_f32 v40, v40, v16, v17
	s_nop 0
	v_max3_f32 v37, v37, v14, v15
	s_nop 0
	v_max_f32_e32 v37, v37, v40
	s_nop 0
	v_mov_b32_e32 v40, v37
	s_nop 1
	v_permlane32_swap_b32_e32 v37, v40
	v_max_f32_e32 v37, v37, v40
	s_nop 0
	v_add_f32_e32 v196, v1, v37
	v_sub_f32_e32 v40, v2, v37
	v_sub_f32_e32 v18, v18, v37
	v_sub_f32_e32 v19, v19, v37
	v_sub_f32_e32 v41, v3, v37
	v_sub_f32_e32 v20, v20, v37
	s_nop 0
	v_xor_b32_e32 v2, 0x80000000, v196
	v_sub_f32_e32 v42, v4, v37
	v_sub_f32_e32 v21, v21, v37
	v_sub_f32_e32 v43, v5, v37
	v_sub_f32_e32 v22, v22, v37
	v_sub_f32_e32 v44, v6, v37
	v_sub_f32_e32 v23, v23, v37
	v_sub_f32_e32 v45, v7, v37
	v_sub_f32_e32 v24, v24, v37
	v_sub_f32_e32 v46, v8, v37
	v_sub_f32_e32 v25, v25, v37
	v_sub_f32_e32 v47, v9, v37
	v_sub_f32_e32 v26, v26, v37
	v_sub_f32_e32 v48, v10, v37
	v_sub_f32_e32 v27, v27, v37
	v_sub_f32_e32 v49, v11, v37
	v_sub_f32_e32 v28, v28, v37
	v_sub_f32_e32 v50, v12, v37
	v_sub_f32_e32 v29, v29, v37
	v_sub_f32_e32 v51, v13, v37
	v_sub_f32_e32 v30, v30, v37
	v_sub_f32_e32 v52, v14, v37
	v_sub_f32_e32 v31, v31, v37
	v_sub_f32_e32 v53, v15, v37
	v_sub_f32_e32 v32, v32, v37
	v_sub_f32_e32 v54, v16, v37
	v_sub_f32_e32 v33, v33, v37
	v_sub_f32_e32 v37, v17, v37
	v_mov_b32_e32 v3, v2
	v_mov_b32_e32 v4, v2
	v_mov_b32_e32 v5, v2
	v_mov_b32_e32 v6, v2
	v_mov_b32_e32 v7, v2
	v_mov_b32_e32 v8, v2
	v_mov_b32_e32 v9, v2
	v_mov_b32_e32 v10, v2
	v_mov_b32_e32 v11, v2
	v_mov_b32_e32 v12, v2
	v_mov_b32_e32 v13, v2
	v_mov_b32_e32 v14, v2
	v_mov_b32_e32 v15, v2
	v_mov_b32_e32 v16, v2
	v_mov_b32_e32 v17, v2
	s_waitcnt vmcnt(0) lgkmcnt(0)
	s_barrier
	v_exp_f32_e32 v55, v18
	v_exp_f32_e32 v56, v19
	v_lshl_add_u64 v[18:19], v[34:35], 0, s[4:5]
	s_mov_b32 s4, m0
	s_mov_b32 m0, s8
	s_nop 0
	global_load_lds_dwordx4 v[18:19], off
	s_mov_b32 m0, s4
	s_mov_b64 s[4:5], 0x80500
	v_lshl_add_u64 v[18:19], v[38:39], 0, s[4:5]
	s_add_i32 s4, s8, 0x8000
	s_mov_b32 s5, m0
	s_mov_b32 m0, s4
	s_nop 0
	global_load_lds_dwordx4 v[18:19], off
	s_mov_b32 m0, s5
	v_exp_f32_e32 v59, v22
	v_exp_f32_e32 v60, v23
	v_exp_f32_e32 v61, v24
	v_exp_f32_e32 v62, v25
	v_exp_f32_e32 v63, v26
	v_exp_f32_e32 v64, v27
	v_exp_f32_e32 v65, v28
	v_exp_f32_e32 v94, v29
	v_exp_f32_e32 v95, v30
	v_exp_f32_e32 v96, v31
	v_exp_f32_e32 v97, v32
	v_exp_f32_e32 v134, v33
	v_exp_f32_e32 v135, v40
	v_exp_f32_e32 v136, v41
	v_exp_f32_e32 v137, v42
	v_exp_f32_e32 v138, v43
	v_exp_f32_e32 v139, v44
	v_exp_f32_e32 v140, v45
	v_exp_f32_e32 v141, v46
	v_exp_f32_e32 v150, v47
	ds_read_b128 v[22:25], v199 offset:8192
	ds_read_b128 v[26:29], v199 offset:8704
	ds_read_b128 v[30:33], v199 offset:10240
	ds_read_b128 v[40:43], v199 offset:10752
	ds_read_b128 v[44:47], v199 offset:12288
	ds_read_b128 v[82:85], v199 offset:12800
	ds_read_b128 v[86:89], v199 offset:14336
	ds_read_b128 v[90:93], v199 offset:14848
	v_exp_f32_e32 v57, v20
	v_exp_f32_e32 v58, v21
	s_waitcnt vmcnt(2) lgkmcnt(0)
	s_barrier
	v_cmp_gt_u32_e64 s[4:5], 32, v189
	v_exp_f32_e32 v48, v48
	v_exp_f32_e32 v49, v49
	v_exp_f32_e32 v151, v50
	v_exp_f32_e32 v152, v51
	v_exp_f32_e32 v153, v52
	v_exp_f32_e32 v154, v53
	v_exp_f32_e32 v155, v54
	v_exp_f32_e32 v156, v37
	ds_read_b64_tr_b16 v[18:19], v198 offset:24576
	ds_read_b64_tr_b16 v[20:21], v198 offset:25088
	s_waitcnt lgkmcnt(9)
	v_mfma_f32_32x32x16_bf16 v[98:113], v[22:25], v[146:149], v[2:17]
	v_add_f32_e32 v34, v55, v56
	v_add_f32_e32 v34, v34, v57
	v_add_f32_e32 v34, v34, v58
	v_add_f32_e32 v34, v34, v59
	v_add_f32_e32 v50, v34, v60
	v_cvt_pk_bf16_f32 v126, v55, v56
	v_cvt_pk_bf16_f32 v127, v57, v58
	ds_read_b64_tr_b16 v[34:35], v198 offset:28672
	ds_read_b64_tr_b16 v[36:37], v198 offset:29184
	s_waitcnt lgkmcnt(10)
	v_mfma_f32_32x32x16_bf16 v[66:81], v[26:29], v[146:149], v[2:17]
	v_add_f32_e32 v22, v61, v50
	v_add_f32_e32 v22, v62, v22
	v_add_f32_e32 v22, v63, v22
	v_add_f32_e32 v22, v64, v22
	v_cvt_pk_bf16_f32 v128, v59, v60
	v_cvt_pk_bf16_f32 v129, v61, v62
	ds_read_b64_tr_b16 v[50:51], v198 offset:25600
	ds_read_b64_tr_b16 v[52:53], v198 offset:26112
	s_waitcnt lgkmcnt(11)
	v_mfma_f32_32x32x16_bf16 v[98:113], v[30:33], v[142:145], v[98:113]
	v_add_f32_e32 v22, v65, v22
	v_add_f32_e32 v22, v94, v22
	v_add_f32_e32 v22, v95, v22
	v_add_f32_e32 v22, v96, v22
	v_cvt_pk_bf16_f32 v122, v63, v64
	v_cvt_pk_bf16_f32 v123, v65, v94
	ds_read_b64_tr_b16 v[54:55], v198 offset:29696
	ds_read_b64_tr_b16 v[56:57], v198 offset:30208
	s_waitcnt lgkmcnt(12)
	v_mfma_f32_32x32x16_bf16 v[66:81], v[40:43], v[142:145], v[66:81]
	v_add_f32_e32 v22, v97, v22
	v_add_f32_e32 v22, v134, v22
	v_add_f32_e32 v22, v135, v22
	v_add_f32_e32 v22, v136, v22
	v_cvt_pk_bf16_f32 v124, v95, v96
	v_cvt_pk_bf16_f32 v125, v97, v134
	ds_read_b64_tr_b16 v[58:59], v198 offset:26624
	ds_read_b64_tr_b16 v[60:61], v198 offset:27136
	s_waitcnt lgkmcnt(13)
	v_mfma_f32_32x32x16_bf16 v[98:113], v[44:47], v[118:121], v[98:113]
	v_add_f32_e32 v22, v137, v22
	v_add_f32_e32 v22, v138, v22
	v_add_f32_e32 v22, v139, v22
	v_add_f32_e32 v22, v140, v22
	v_cvt_pk_bf16_f32 v134, v135, v136
	v_cvt_pk_bf16_f32 v135, v137, v138
	ds_read_b64_tr_b16 v[62:63], v198 offset:30720
	ds_read_b64_tr_b16 v[64:65], v198 offset:31232
	s_waitcnt lgkmcnt(14)
	v_mfma_f32_32x32x16_bf16 v[66:81], v[82:85], v[118:121], v[66:81]
	v_add_f32_e32 v22, v141, v22
	v_add_f32_e32 v22, v150, v22
	v_add_f32_e32 v22, v48, v22
	v_add_f32_e32 v22, v49, v22
	v_cvt_pk_bf16_f32 v136, v139, v140
	v_cvt_pk_bf16_f32 v137, v141, v150
	ds_read_b64_tr_b16 v[82:83], v198 offset:27648
	ds_read_b64_tr_b16 v[84:85], v198 offset:28160
	s_waitcnt lgkmcnt(14)
	v_mfma_f32_32x32x16_bf16 v[98:113], v[86:89], v[114:117], v[98:113]
	v_add_f32_e32 v22, v151, v22
	v_add_f32_e32 v22, v152, v22
	v_add_f32_e32 v22, v153, v22
	v_add_f32_e32 v22, v154, v22
	v_cvt_pk_bf16_f32 v138, v48, v49
	v_cvt_pk_bf16_f32 v139, v151, v152
	ds_read_b64_tr_b16 v[86:87], v198 offset:31744
	ds_read_b64_tr_b16 v[88:89], v198 offset:32256
	v_mfma_f32_32x32x16_bf16 v[66:81], v[90:93], v[114:117], v[66:81]
	v_add_f32_e32 v22, v155, v22
	v_add_f32_e32 v22, v156, v22
	s_nop 0
	v_cvt_pk_bf16_f32 v140, v153, v154
	v_cvt_pk_bf16_f32 v141, v155, v156
	s_mov_b64 s[10:11], 0x100500
	v_add_f32_e32 v200, 0, v22
	v_lshl_add_u64 v[22:23], v[38:39], 0, s[10:11]
	s_add_i32 s8, s8, 0xa000
	s_mov_b32 s9, m0
	s_mov_b32 m0, s8
	s_nop 0
	global_load_lds_dwordx4 v[22:23], off
	s_mov_b32 m0, s9
	v_max_f32_e32 v22, v99, v98
	s_nop 1
	v_max3_f32 v23, v100, v101, v67
	v_max3_f32 v22, v22, v66, v68
	v_max3_f32 v22, v22, v69, v102
	v_max3_f32 v23, v23, v104, v105
	v_max3_f32 v22, v22, v103, v70
	v_max3_f32 v23, v23, v72, v73
	v_max3_f32 v22, v22, v71, v106
	v_max3_f32 v23, v23, v108, v109
	v_max3_f32 v22, v22, v107, v74
	v_max3_f32 v23, v23, v76, v77
	v_max3_f32 v22, v22, v75, v110
	v_max3_f32 v23, v23, v112, v113
	v_max3_f32 v22, v22, v111, v78
	v_max3_f32 v23, v23, v80, v81
	v_max3_f32 v22, v22, v79, v23
	v_mov_b32_e32 v23, v22
	s_nop 1
	v_permlane32_swap_b32_e32 v22, v23
	s_nop 1
	v_max_f32_e32 v22, v22, v23
	v_cmp_lt_f32_e32 vcc, s22, v22
	s_cmp_lg_u64 vcc, 0
	s_cselect_b64 s[8:9], -1, 0
	s_cbranch_vccnz .LBB0_997

.LBB0_889:
	ds_read_b64_tr_b16 v[154:155], v198 offset:32768
	ds_read_b64_tr_b16 v[156:157], v198 offset:33280
	s_waitcnt lgkmcnt(9)
	v_mfma_f32_32x32x16_bf16 v[82:97], v[150:153], v[146:149], v[2:17]
	v_add_f32_e32 v50, v98, v99
	v_add_f32_e32 v50, v100, v50
	v_add_f32_e32 v50, v101, v50
	v_add_f32_e32 v50, v102, v50
	v_add_f32_e32 v50, v103, v50
	v_cvt_pk_bf16_f32 v126, v98, v99
	v_cvt_pk_bf16_f32 v127, v100, v101
	ds_read_b64_tr_b16 v[150:151], v198 offset:36864
	ds_read_b64_tr_b16 v[152:153], v198 offset:37376
	v_add_f32_e32 v50, v104, v50
	v_add_f32_e32 v50, v105, v50
	v_add_f32_e32 v50, v106, v50
	v_add_f32_e32 v122, v107, v50
	s_waitcnt lgkmcnt(10)
	v_mfma_f32_32x32x16_bf16 v[50:65], v[178:181], v[146:149], v[2:17]
	v_cvt_pk_bf16_f32 v128, v102, v103
	v_cvt_pk_bf16_f32 v129, v104, v105
	ds_read_b64_tr_b16 v[98:99], v198 offset:33792
	ds_read_b64_tr_b16 v[100:101], v198 offset:34304
	s_waitcnt lgkmcnt(11)
	v_mfma_f32_32x32x16_bf16 v[82:97], v[182:185], v[142:145], v[82:97]
	v_add_f32_e32 v102, v108, v122
	v_add_f32_e32 v102, v109, v102
	v_add_f32_e32 v102, v110, v102
	v_add_f32_e32 v134, v111, v102
	v_cvt_pk_bf16_f32 v122, v106, v107
	v_cvt_pk_bf16_f32 v123, v108, v109
	ds_read_b64_tr_b16 v[102:103], v198 offset:37888
	ds_read_b64_tr_b16 v[104:105], v198 offset:38400
	s_waitcnt lgkmcnt(12)
	v_mfma_f32_32x32x16_bf16 v[50:65], v[174:177], v[142:145], v[50:65]
	v_add_f32_e32 v106, v112, v134
	v_add_f32_e32 v106, v113, v106
	v_add_f32_e32 v106, v66, v106
	v_add_f32_e32 v134, v67, v106
	v_cvt_pk_bf16_f32 v124, v110, v111
	v_cvt_pk_bf16_f32 v125, v112, v113
	ds_read_b64_tr_b16 v[106:107], v198 offset:34816
	ds_read_b64_tr_b16 v[108:109], v198 offset:35328
	s_waitcnt lgkmcnt(13)
	v_mfma_f32_32x32x16_bf16 v[82:97], v[170:173], v[118:121], v[82:97]
	v_add_f32_e32 v110, v68, v134
	v_add_f32_e32 v110, v69, v110
	v_add_f32_e32 v110, v70, v110
	v_add_f32_e32 v110, v71, v110
	v_cvt_pk_bf16_f32 v134, v66, v67
	v_cvt_pk_bf16_f32 v135, v68, v69
	ds_read_b64_tr_b16 v[66:67], v198 offset:38912
	ds_read_b64_tr_b16 v[68:69], v198 offset:39424
	s_waitcnt lgkmcnt(14)
	v_mfma_f32_32x32x16_bf16 v[50:65], v[166:169], v[118:121], v[50:65]
	v_add_f32_e32 v110, v72, v110
	v_add_f32_e32 v110, v73, v110
	v_add_f32_e32 v110, v74, v110
	v_add_f32_e32 v110, v75, v110
	v_cvt_pk_bf16_f32 v136, v70, v71
	v_cvt_pk_bf16_f32 v137, v72, v73
	ds_read_b64_tr_b16 v[70:71], v198 offset:35840
	ds_read_b64_tr_b16 v[72:73], v198 offset:36352
	s_waitcnt lgkmcnt(14)
	v_mfma_f32_32x32x16_bf16 v[82:97], v[162:165], v[114:117], v[82:97]
	v_add_f32_e32 v110, v76, v110
	v_add_f32_e32 v110, v77, v110
	v_add_f32_e32 v110, v78, v110
	v_add_f32_e32 v110, v79, v110
	v_cvt_pk_bf16_f32 v138, v74, v75
	v_cvt_pk_bf16_f32 v139, v76, v77
	ds_read_b64_tr_b16 v[74:75], v198 offset:39936
	ds_read_b64_tr_b16 v[76:77], v198 offset:40448
	v_mfma_f32_32x32x16_bf16 v[50:65], v[158:161], v[114:117], v[50:65]
	v_add_f32_e32 v110, v80, v110
	v_add_f32_e32 v110, v81, v110
	s_nop 0
	v_cvt_pk_bf16_f32 v140, v78, v79
	v_cvt_pk_bf16_f32 v141, v80, v81
	s_mov_b64 s[8:9], 0x180000
	v_lshl_add_u64 v[78:79], v[186:187], 0, s[8:9]
	s_mov_b32 s8, m0
	s_mov_b32 m0, s18
	s_nop 0
	global_load_lds_dwordx4 v[78:79], off
	s_mov_b32 m0, s8
	v_max_f32_e32 v78, v83, v82
	s_nop 3
	v_max3_f32 v79, v84, v85, v51
	v_max3_f32 v78, v78, v50, v52
	v_max3_f32 v78, v78, v53, v86
	v_max3_f32 v79, v79, v88, v89
	v_max3_f32 v78, v78, v87, v54
	v_max3_f32 v79, v79, v56, v57
	v_max3_f32 v78, v78, v55, v90
	v_max3_f32 v79, v79, v92, v93
	v_max3_f32 v78, v78, v91, v58
	v_max3_f32 v79, v79, v60, v61
	v_max3_f32 v78, v78, v59, v94
	v_max3_f32 v79, v79, v96, v97
	v_max3_f32 v78, v78, v95, v62
	v_max3_f32 v79, v79, v64, v65
	v_max3_f32 v78, v78, v63, v79
	v_mov_b32_e32 v79, v78
	s_nop 1
	v_permlane32_swap_b32_e32 v78, v79
	s_nop 1
	v_max_f32_e32 v78, v78, v79
	v_cmp_lt_f32_e32 vcc, s22, v78
	s_cmp_lg_u64 vcc, 0
	v_add_f32_e32 v174, v200, v110
	s_cselect_b64 s[8:9], -1, 0
	s_cbranch_vccnz .LBB0_1000

.LBB0_892:
	ds_read_b64_tr_b16 v[98:99], v198 offset:40960
	ds_read_b64_tr_b16 v[100:101], v198 offset:41472
	v_add_f32_e32 v66, v82, v83
	v_add_f32_e32 v66, v84, v66
	v_add_f32_e32 v66, v85, v66
	v_add_f32_e32 v66, v86, v66
	v_add_f32_e32 v106, v87, v66
	s_waitcnt lgkmcnt(9)
	v_mfma_f32_32x32x16_bf16 v[66:81], v[170:173], v[146:149], v[2:17]
	v_cvt_pk_bf16_f32 v126, v82, v83
	v_cvt_pk_bf16_f32 v127, v84, v85
	ds_read_b64_tr_b16 v[82:83], v198 offset:45056
	ds_read_b64_tr_b16 v[84:85], v198 offset:45568
	s_waitcnt lgkmcnt(10)
	v_mfma_f32_32x32x16_bf16 v[2:17], v[166:169], v[146:149], v[2:17]
	v_add_f32_e32 v106, v88, v106
	v_add_f32_e32 v106, v89, v106
	v_add_f32_e32 v106, v90, v106
	v_add_f32_e32 v106, v91, v106
	v_cvt_pk_bf16_f32 v128, v86, v87
	v_cvt_pk_bf16_f32 v129, v88, v89
	ds_read_b64_tr_b16 v[86:87], v198 offset:41984
	ds_read_b64_tr_b16 v[88:89], v198 offset:42496
	s_waitcnt lgkmcnt(11)
	v_mfma_f32_32x32x16_bf16 v[66:81], v[162:165], v[142:145], v[66:81]
	v_add_f32_e32 v106, v92, v106
	v_add_f32_e32 v106, v93, v106
	v_add_f32_e32 v106, v94, v106
	v_add_f32_e32 v106, v95, v106
	v_cvt_pk_bf16_f32 v122, v90, v91
	v_cvt_pk_bf16_f32 v123, v92, v93
	ds_read_b64_tr_b16 v[90:91], v198 offset:46080
	ds_read_b64_tr_b16 v[92:93], v198 offset:46592
	s_waitcnt lgkmcnt(12)
	v_mfma_f32_32x32x16_bf16 v[2:17], v[158:161], v[142:145], v[2:17]
	v_add_f32_e32 v106, v96, v106
	v_add_f32_e32 v106, v97, v106
	v_add_f32_e32 v106, v50, v106
	v_add_f32_e32 v106, v51, v106
	v_cvt_pk_bf16_f32 v124, v94, v95
	v_cvt_pk_bf16_f32 v125, v96, v97
	ds_read_b64_tr_b16 v[94:95], v198 offset:43008
	ds_read_b64_tr_b16 v[96:97], v198 offset:43520
	s_waitcnt lgkmcnt(13)
	v_mfma_f32_32x32x16_bf16 v[66:81], v[102:105], v[118:121], v[66:81]
	v_add_f32_e32 v102, v52, v106
	v_add_f32_e32 v102, v53, v102
	v_add_f32_e32 v102, v54, v102
	v_add_f32_e32 v106, v55, v102
	v_cvt_pk_bf16_f32 v134, v50, v51
	v_cvt_pk_bf16_f32 v135, v52, v53
	ds_read_b64_tr_b16 v[102:103], v198 offset:47104
	ds_read_b64_tr_b16 v[104:105], v198 offset:47616
	s_waitcnt lgkmcnt(14)
	v_mfma_f32_32x32x16_bf16 v[2:17], v[154:157], v[118:121], v[2:17]
	v_add_f32_e32 v50, v56, v106
	v_add_f32_e32 v50, v57, v50
	v_add_f32_e32 v50, v58, v50
	v_add_f32_e32 v50, v59, v50
	v_cvt_pk_bf16_f32 v136, v54, v55
	v_cvt_pk_bf16_f32 v137, v56, v57
	ds_read_b64_tr_b16 v[106:107], v198 offset:44032
	ds_read_b64_tr_b16 v[108:109], v198 offset:44544
	s_waitcnt lgkmcnt(14)
	v_mfma_f32_32x32x16_bf16 v[66:81], v[150:153], v[114:117], v[66:81]
	v_add_f32_e32 v50, v60, v50
	v_add_f32_e32 v50, v61, v50
	v_add_f32_e32 v50, v62, v50
	v_add_f32_e32 v50, v63, v50
	v_cvt_pk_bf16_f32 v138, v58, v59
	v_cvt_pk_bf16_f32 v139, v60, v61
	ds_read_b64_tr_b16 v[118:119], v198 offset:48128
	ds_read_b64_tr_b16 v[120:121], v198 offset:48640
	v_mfma_f32_32x32x16_bf16 v[2:17], v[110:113], v[114:117], v[2:17]
	v_add_f32_e32 v50, v64, v50
	v_add_f32_e32 v50, v65, v50
	s_nop 0
	v_cvt_pk_bf16_f32 v140, v62, v63
	v_cvt_pk_bf16_f32 v141, v64, v65
	v_max_f32_e32 v51, v67, v66
	s_nop 5
	v_max3_f32 v52, v68, v69, v3
	v_max3_f32 v51, v51, v2, v4
	v_max3_f32 v51, v51, v5, v70
	v_max3_f32 v52, v52, v72, v73
	v_max3_f32 v51, v51, v71, v6
	v_max3_f32 v52, v52, v8, v9
	v_max3_f32 v51, v51, v7, v74
	v_max3_f32 v52, v52, v76, v77
	v_max3_f32 v51, v51, v75, v10
	v_max3_f32 v52, v52, v12, v13
	v_max3_f32 v51, v51, v11, v78
	v_max3_f32 v52, v52, v80, v81
	v_max3_f32 v51, v51, v79, v14
	v_max3_f32 v52, v52, v16, v17
	v_add_f32_e32 v110, v174, v50
	v_max3_f32 v50, v51, v15, v52
	v_mov_b32_e32 v51, v50
	s_nop 1
	v_permlane32_swap_b32_e32 v50, v51
	s_nop 1
	v_max_f32_e32 v50, v50, v51
	v_cmp_lt_f32_e32 vcc, s22, v50
	s_cmp_lg_u64 vcc, 0
	s_cselect_b64 s[8:9], -1, 0
	s_cbranch_vccnz .LBB0_1003

.LBB0_933:
	v_add_u32_e32 v191, s10, v206
	ds_read_b64_tr_b16 v[182:183], v191 offset:24576
	ds_read_b64_tr_b16 v[184:185], v191 offset:25088
	s_waitcnt lgkmcnt(9)
	v_mfma_f32_32x32x16_bf16 v[98:113], v[82:85], v[162:165], v[34:49]
	v_add_f32_e32 v86, v66, v67
	v_add_f32_e32 v86, v68, v86
	v_add_f32_e32 v86, v69, v86
	v_add_f32_e32 v86, v70, v86
	v_add_f32_e32 v86, v71, v86
	v_cvt_pk_bf16_f32 v154, v66, v67
	v_cvt_pk_bf16_f32 v155, v68, v69
	ds_read_b64_tr_b16 v[178:179], v191 offset:28672
	ds_read_b64_tr_b16 v[180:181], v191 offset:29184
	v_add_f32_e32 v66, v72, v86
	s_waitcnt lgkmcnt(10)
	v_mfma_f32_32x32x16_bf16 v[82:97], v[170:173], v[162:165], v[34:49]
	v_add_f32_e32 v66, v73, v66
	v_add_f32_e32 v66, v74, v66
	v_add_f32_e32 v134, v75, v66
	v_cvt_pk_bf16_f32 v156, v70, v71
	v_cvt_pk_bf16_f32 v157, v72, v73
	ds_read_b64_tr_b16 v[66:67], v191 offset:25600
	ds_read_b64_tr_b16 v[68:69], v191 offset:26112
	s_waitcnt lgkmcnt(11)
	v_mfma_f32_32x32x16_bf16 v[98:113], v[174:177], v[158:161], v[98:113]
	v_add_f32_e32 v70, v76, v134
	v_add_f32_e32 v70, v77, v70
	v_add_f32_e32 v70, v78, v70
	v_add_f32_e32 v134, v79, v70
	v_cvt_pk_bf16_f32 v146, v74, v75
	v_cvt_pk_bf16_f32 v147, v76, v77
	ds_read_b64_tr_b16 v[70:71], v191 offset:29696
	ds_read_b64_tr_b16 v[72:73], v191 offset:30208
	s_waitcnt lgkmcnt(12)
	v_mfma_f32_32x32x16_bf16 v[82:97], v[166:169], v[158:161], v[82:97]
	v_add_f32_e32 v74, v80, v134
	v_add_f32_e32 v74, v81, v74
	v_add_f32_e32 v74, v50, v74
	v_add_f32_e32 v134, v51, v74
	v_cvt_pk_bf16_f32 v148, v78, v79
	v_cvt_pk_bf16_f32 v149, v80, v81
	ds_read_b64_tr_b16 v[74:75], v191 offset:26624
	ds_read_b64_tr_b16 v[76:77], v191 offset:27136
	s_waitcnt lgkmcnt(13)
	v_mfma_f32_32x32x16_bf16 v[98:113], v[126:129], v[150:153], v[98:113]
	v_add_f32_e32 v78, v52, v134
	v_add_f32_e32 v78, v53, v78
	v_add_f32_e32 v78, v54, v78
	v_add_f32_e32 v78, v55, v78
	v_cvt_pk_bf16_f32 v138, v50, v51
	v_cvt_pk_bf16_f32 v139, v52, v53
	ds_read_b64_tr_b16 v[50:51], v191 offset:30720
	ds_read_b64_tr_b16 v[52:53], v191 offset:31232
	s_waitcnt lgkmcnt(14)
	v_mfma_f32_32x32x16_bf16 v[82:97], v[122:125], v[150:153], v[82:97]
	v_add_f32_e32 v78, v56, v78
	v_add_f32_e32 v78, v57, v78
	v_add_f32_e32 v78, v58, v78
	v_add_f32_e32 v78, v59, v78
	v_cvt_pk_bf16_f32 v140, v54, v55
	v_cvt_pk_bf16_f32 v141, v56, v57
	ds_read_b64_tr_b16 v[54:55], v191 offset:27648
	ds_read_b64_tr_b16 v[56:57], v191 offset:28160
	s_waitcnt lgkmcnt(14)
	v_mfma_f32_32x32x16_bf16 v[98:113], v[118:121], v[142:145], v[98:113]
	v_add_f32_e32 v78, v60, v78
	v_add_f32_e32 v78, v61, v78
	v_add_f32_e32 v78, v62, v78
	v_add_f32_e32 v78, v63, v78
	v_cvt_pk_bf16_f32 v134, v58, v59
	v_cvt_pk_bf16_f32 v135, v60, v61
	ds_read_b64_tr_b16 v[58:59], v191 offset:31744
	ds_read_b64_tr_b16 v[60:61], v191 offset:32256
	v_mfma_f32_32x32x16_bf16 v[82:97], v[114:117], v[142:145], v[82:97]
	v_add_f32_e32 v78, v64, v78
	v_add_f32_e32 v78, v65, v78
	s_nop 0
	v_cvt_pk_bf16_f32 v136, v62, v63
	v_cvt_pk_bf16_f32 v137, v64, v65
	v_lshl_add_u64 v[62:63], v[188:189], 0, s[92:93]
	s_add_i32 s10, s31, s26
	s_mov_b32 s11, m0
	s_mov_b32 m0, s10
	s_nop 0
	global_load_lds_dwordx4 v[62:63], off
	s_mov_b32 m0, s11
	v_lshl_add_u64 v[62:63], v[186:187], 0, s[92:93]
	s_add_i32 s10, s30, s19
	s_mov_b32 s11, m0
	s_mov_b32 m0, s10
	s_nop 0
	global_load_lds_dwordx4 v[62:63], off
	s_mov_b32 m0, s11
	v_max_f32_e32 v62, v99, v98
	s_nop 1
	v_max3_f32 v63, v100, v101, v83
	v_max3_f32 v62, v62, v82, v84
	v_max3_f32 v62, v62, v85, v102
	v_max3_f32 v63, v63, v104, v105
	v_max3_f32 v62, v62, v103, v86
	v_max3_f32 v63, v63, v88, v89
	v_max3_f32 v62, v62, v87, v106
	v_max3_f32 v63, v63, v108, v109
	v_max3_f32 v62, v62, v107, v90
	v_max3_f32 v63, v63, v92, v93
	v_max3_f32 v62, v62, v91, v110
	v_max3_f32 v63, v63, v112, v113
	v_max3_f32 v62, v62, v111, v94
	v_max3_f32 v63, v63, v96, v97
	v_max3_f32 v62, v62, v95, v63
	v_mov_b32_e32 v63, v62
	s_nop 1
	v_permlane32_swap_b32_e32 v62, v63
	s_nop 1
	v_max_f32_e32 v62, v62, v63
	v_cmp_lt_f32_e32 vcc, s22, v62
	s_cmp_lg_u64 vcc, 0
	v_add_f32_e32 v190, v190, v78
	s_cselect_b64 s[10:11], -1, 0
	s_cbranch_vccnz .LBB0_941

.LBB0_936:
	s_add_i32 s10, s30, 0x2000
	s_cmpk_lg_i32 s30, 0x4000
	s_cselect_b32 s40, s10, 0
	v_add_u32_e32 v191, s31, v206
	ds_read_b64_tr_b16 v[118:119], v191 offset:24576
	ds_read_b64_tr_b16 v[120:121], v191 offset:25088
	s_waitcnt lgkmcnt(9)
	v_mfma_f32_32x32x16_bf16 v[66:81], v[62:65], v[162:165], v[34:49]
	v_add_f32_e32 v50, v98, v99
	v_add_f32_e32 v50, v100, v50
	v_add_f32_e32 v50, v101, v50
	v_add_f32_e32 v50, v102, v50
	v_add_f32_e32 v50, v103, v50
	v_cvt_pk_bf16_f32 v154, v98, v99
	v_cvt_pk_bf16_f32 v155, v100, v101
	ds_read_b64_tr_b16 v[114:115], v191 offset:28672
	ds_read_b64_tr_b16 v[116:117], v191 offset:29184
	v_add_f32_e32 v50, v104, v50
	v_add_f32_e32 v50, v105, v50
	v_add_f32_e32 v50, v106, v50
	v_add_f32_e32 v134, v107, v50
	s_waitcnt lgkmcnt(10)
	v_mfma_f32_32x32x16_bf16 v[50:65], v[178:181], v[162:165], v[34:49]
	v_cvt_pk_bf16_f32 v156, v102, v103
	v_cvt_pk_bf16_f32 v157, v104, v105
	ds_read_b64_tr_b16 v[98:99], v191 offset:25600
	ds_read_b64_tr_b16 v[100:101], v191 offset:26112
	s_waitcnt lgkmcnt(11)
	v_mfma_f32_32x32x16_bf16 v[66:81], v[182:185], v[158:161], v[66:81]
	v_add_f32_e32 v102, v108, v134
	v_add_f32_e32 v102, v109, v102
	v_add_f32_e32 v102, v110, v102
	v_add_f32_e32 v134, v111, v102
	v_cvt_pk_bf16_f32 v146, v106, v107
	v_cvt_pk_bf16_f32 v147, v108, v109
	ds_read_b64_tr_b16 v[102:103], v191 offset:29696
	ds_read_b64_tr_b16 v[104:105], v191 offset:30208
	s_waitcnt lgkmcnt(12)
	v_mfma_f32_32x32x16_bf16 v[50:65], v[174:177], v[158:161], v[50:65]
	v_add_f32_e32 v106, v112, v134
	v_add_f32_e32 v106, v113, v106
	v_add_f32_e32 v106, v82, v106
	v_add_f32_e32 v134, v83, v106
	v_cvt_pk_bf16_f32 v148, v110, v111
	v_cvt_pk_bf16_f32 v149, v112, v113
	ds_read_b64_tr_b16 v[106:107], v191 offset:26624
	ds_read_b64_tr_b16 v[108:109], v191 offset:27136
	s_waitcnt lgkmcnt(13)
	v_mfma_f32_32x32x16_bf16 v[66:81], v[170:173], v[150:153], v[66:81]
	v_add_f32_e32 v110, v84, v134
	v_add_f32_e32 v110, v85, v110
	v_add_f32_e32 v110, v86, v110
	v_add_f32_e32 v134, v87, v110
	v_cvt_pk_bf16_f32 v138, v82, v83
	v_cvt_pk_bf16_f32 v139, v84, v85
	ds_read_b64_tr_b16 v[110:111], v191 offset:30720
	ds_read_b64_tr_b16 v[112:113], v191 offset:31232
	s_waitcnt lgkmcnt(14)
	v_mfma_f32_32x32x16_bf16 v[50:65], v[166:169], v[150:153], v[50:65]
	v_add_f32_e32 v82, v88, v134
	v_add_f32_e32 v82, v89, v82
	v_add_f32_e32 v82, v90, v82
	v_add_f32_e32 v82, v91, v82
	v_cvt_pk_bf16_f32 v140, v86, v87
	v_cvt_pk_bf16_f32 v141, v88, v89
	ds_read_b64_tr_b16 v[86:87], v191 offset:27648
	ds_read_b64_tr_b16 v[88:89], v191 offset:28160
	s_waitcnt lgkmcnt(14)
	v_mfma_f32_32x32x16_bf16 v[66:81], v[126:129], v[142:145], v[66:81]
	v_add_f32_e32 v82, v92, v82
	v_add_f32_e32 v82, v93, v82
	v_add_f32_e32 v82, v94, v82
	v_add_f32_e32 v82, v95, v82
	v_cvt_pk_bf16_f32 v134, v90, v91
	v_cvt_pk_bf16_f32 v135, v92, v93
	ds_read_b64_tr_b16 v[90:91], v191 offset:31744
	ds_read_b64_tr_b16 v[92:93], v191 offset:32256
	v_mfma_f32_32x32x16_bf16 v[50:65], v[122:125], v[142:145], v[50:65]
	v_add_f32_e32 v82, v96, v82
	v_add_f32_e32 v82, v97, v82
	s_nop 0
	v_cvt_pk_bf16_f32 v136, v94, v95
	v_cvt_pk_bf16_f32 v137, v96, v97
	v_max_f32_e32 v83, v67, v66
	s_nop 5
	v_max3_f32 v84, v68, v69, v51
	v_max3_f32 v83, v83, v50, v52
	v_max3_f32 v83, v83, v53, v70
	v_max3_f32 v84, v84, v72, v73
	v_max3_f32 v83, v83, v71, v54
	v_max3_f32 v84, v84, v56, v57
	v_max3_f32 v83, v83, v55, v74
	v_max3_f32 v84, v84, v76, v77
	v_max3_f32 v83, v83, v75, v58
	v_max3_f32 v84, v84, v60, v61
	v_max3_f32 v83, v83, v59, v78
	v_max3_f32 v84, v84, v80, v81
	v_max3_f32 v83, v83, v79, v62
	v_max3_f32 v84, v84, v64, v65
	v_add_f32_e32 v190, v190, v82
	v_max3_f32 v82, v83, v63, v84
	v_mov_b32_e32 v83, v82
	s_nop 1
	v_permlane32_swap_b32_e32 v82, v83
	v_max_f32_e32 v83, v83, v83
	v_max_f32_e32 v82, v82, v82
	s_add_i32 s10, s30, s26
	s_mov_b32 s11, m0
	s_mov_b32 m0, s10
	s_nop 0
	global_load_lds_dwordx4 v[188:189], off
	s_mov_b32 m0, s11
	v_max_f32_e32 v82, v82, v83
	s_add_i32 s10, s40, s19
	s_mov_b32 s11, m0
	s_mov_b32 m0, s10
	s_nop 0
	global_load_lds_dwordx4 v[186:187], off
	s_mov_b32 m0, s11
	v_cmp_lt_f32_e32 vcc, s22, v82
	s_cmp_lg_u64 vcc, 0
	s_cselect_b64 s[10:11], -1, 0
	s_cbranch_vccnz .LBB0_944

.LBB0_947:
	ds_read_b64_tr_b16 v[182:183], v206 offset:24576
	ds_read_b64_tr_b16 v[184:185], v206 offset:25088
	s_waitcnt lgkmcnt(9)
	v_mfma_f32_32x32x16_bf16 v[98:113], v[82:85], v[162:165], v[34:49]
	v_add_f32_e32 v86, v66, v67
	v_add_f32_e32 v86, v68, v86
	v_add_f32_e32 v86, v69, v86
	v_add_f32_e32 v86, v70, v86
	v_add_f32_e32 v86, v71, v86
	v_cvt_pk_bf16_f32 v154, v66, v67
	v_cvt_pk_bf16_f32 v155, v68, v69
	ds_read_b64_tr_b16 v[178:179], v206 offset:28672
	ds_read_b64_tr_b16 v[180:181], v206 offset:29184
	v_add_f32_e32 v66, v72, v86
	s_waitcnt lgkmcnt(10)
	v_mfma_f32_32x32x16_bf16 v[82:97], v[170:173], v[162:165], v[34:49]
	v_add_f32_e32 v66, v73, v66
	v_add_f32_e32 v66, v74, v66
	v_add_f32_e32 v134, v75, v66
	v_cvt_pk_bf16_f32 v156, v70, v71
	v_cvt_pk_bf16_f32 v157, v72, v73
	ds_read_b64_tr_b16 v[66:67], v206 offset:25600
	ds_read_b64_tr_b16 v[68:69], v206 offset:26112
	s_waitcnt lgkmcnt(11)
	v_mfma_f32_32x32x16_bf16 v[98:113], v[174:177], v[158:161], v[98:113]
	v_add_f32_e32 v70, v76, v134
	v_add_f32_e32 v70, v77, v70
	v_add_f32_e32 v70, v78, v70
	v_add_f32_e32 v134, v79, v70
	v_cvt_pk_bf16_f32 v146, v74, v75
	v_cvt_pk_bf16_f32 v147, v76, v77
	ds_read_b64_tr_b16 v[70:71], v206 offset:29696
	ds_read_b64_tr_b16 v[72:73], v206 offset:30208
	s_waitcnt lgkmcnt(12)
	v_mfma_f32_32x32x16_bf16 v[82:97], v[166:169], v[158:161], v[82:97]
	v_add_f32_e32 v74, v80, v134
	v_add_f32_e32 v74, v81, v74
	v_add_f32_e32 v74, v50, v74
	v_add_f32_e32 v134, v51, v74
	v_cvt_pk_bf16_f32 v148, v78, v79
	v_cvt_pk_bf16_f32 v149, v80, v81
	ds_read_b64_tr_b16 v[74:75], v206 offset:26624
	ds_read_b64_tr_b16 v[76:77], v206 offset:27136
	s_waitcnt lgkmcnt(13)
	v_mfma_f32_32x32x16_bf16 v[98:113], v[126:129], v[150:153], v[98:113]
	v_add_f32_e32 v78, v52, v134
	v_add_f32_e32 v78, v53, v78
	v_add_f32_e32 v78, v54, v78
	v_add_f32_e32 v78, v55, v78
	v_cvt_pk_bf16_f32 v138, v50, v51
	v_cvt_pk_bf16_f32 v139, v52, v53
	ds_read_b64_tr_b16 v[50:51], v206 offset:30720
	ds_read_b64_tr_b16 v[52:53], v206 offset:31232
	s_waitcnt lgkmcnt(14)
	v_mfma_f32_32x32x16_bf16 v[82:97], v[122:125], v[150:153], v[82:97]
	v_add_f32_e32 v78, v56, v78
	v_add_f32_e32 v78, v57, v78
	v_add_f32_e32 v78, v58, v78
	v_add_f32_e32 v78, v59, v78
	v_cvt_pk_bf16_f32 v140, v54, v55
	v_cvt_pk_bf16_f32 v141, v56, v57
	ds_read_b64_tr_b16 v[54:55], v206 offset:27648
	ds_read_b64_tr_b16 v[56:57], v206 offset:28160
	s_waitcnt lgkmcnt(14)
	v_mfma_f32_32x32x16_bf16 v[98:113], v[118:121], v[142:145], v[98:113]
	v_add_f32_e32 v78, v60, v78
	v_add_f32_e32 v78, v61, v78
	v_add_f32_e32 v78, v62, v78
	v_add_f32_e32 v78, v63, v78
	v_cvt_pk_bf16_f32 v134, v58, v59
	v_cvt_pk_bf16_f32 v135, v60, v61
	ds_read_b64_tr_b16 v[58:59], v206 offset:31744
	ds_read_b64_tr_b16 v[60:61], v206 offset:32256
	v_mfma_f32_32x32x16_bf16 v[82:97], v[114:117], v[142:145], v[82:97]
	v_add_f32_e32 v78, v64, v78
	v_add_f32_e32 v78, v65, v78
	s_nop 0
	v_cvt_pk_bf16_f32 v136, v62, v63
	v_cvt_pk_bf16_f32 v137, v64, v65
	s_mov_b64 s[10:11], 0x1100000
	s_cmp_lg_u32 0, -1
	v_lshl_add_u64 v[62:63], v[196:197], 0, s[10:11]
	s_cselect_b32 s10, 0, 0
	s_add_i32 s26, s10, s18
	s_add_i32 s10, s26, 0x2000
	s_mov_b32 s11, m0
	s_mov_b32 m0, s10
	s_nop 0
	global_load_lds_dwordx4 v[62:63], off
	s_mov_b32 m0, s11
	s_mov_b64 s[10:11], 0x1000000
	v_lshl_add_u64 v[62:63], v[194:195], 0, s[10:11]
	s_add_i32 s26, s26, 0xa000
	s_mov_b32 s10, m0
	s_mov_b32 m0, s26
	s_nop 0
	global_load_lds_dwordx4 v[62:63], off
	s_mov_b32 m0, s10
	v_max_f32_e32 v62, v99, v98
	s_nop 1
	v_max3_f32 v63, v100, v101, v83
	v_max3_f32 v62, v62, v82, v84
	v_max3_f32 v62, v62, v85, v102
	v_max3_f32 v63, v63, v104, v105
	v_max3_f32 v62, v62, v103, v86
	v_max3_f32 v63, v63, v88, v89
	v_max3_f32 v62, v62, v87, v106
	v_max3_f32 v63, v63, v108, v109
	v_max3_f32 v62, v62, v107, v90
	v_max3_f32 v63, v63, v92, v93
	v_max3_f32 v62, v62, v91, v110
	v_max3_f32 v63, v63, v112, v113
	v_max3_f32 v62, v62, v111, v94
	v_max3_f32 v63, v63, v96, v97
	v_max3_f32 v62, v62, v95, v63
	v_mov_b32_e32 v63, v62
	s_nop 1
	v_permlane32_swap_b32_e32 v62, v63
	s_nop 1
	v_max_f32_e32 v62, v62, v63
	v_cmp_lt_f32_e32 vcc, s22, v62
	s_cmp_lg_u64 vcc, 0
	v_add_f32_e32 v209, v190, v78
	s_cselect_b64 s[10:11], -1, 0
	s_cbranch_vccnz .LBB0_973

.LBB0_950:
	ds_read_b64_tr_b16 v[166:167], v206 offset:32768
	ds_read_b64_tr_b16 v[168:169], v206 offset:33280
	s_waitcnt lgkmcnt(9)
	v_mfma_f32_32x32x16_bf16 v[114:129], v[62:65], v[162:165], v[34:49]
	v_add_f32_e32 v50, v98, v99
	v_add_f32_e32 v50, v100, v50
	v_add_f32_e32 v50, v101, v50
	v_add_f32_e32 v50, v102, v50
	v_add_f32_e32 v50, v103, v50
	v_cvt_pk_bf16_f32 v154, v98, v99
	v_cvt_pk_bf16_f32 v155, v100, v101
	ds_read_b64_tr_b16 v[74:75], v206 offset:36864
	ds_read_b64_tr_b16 v[76:77], v206 offset:37376
	v_add_f32_e32 v50, v104, v50
	v_add_f32_e32 v50, v105, v50
	v_add_f32_e32 v50, v106, v50
	v_add_f32_e32 v70, v107, v50
	s_waitcnt lgkmcnt(10)
	v_mfma_f32_32x32x16_bf16 v[50:65], v[186:189], v[162:165], v[34:49]
	v_cvt_pk_bf16_f32 v156, v102, v103
	v_cvt_pk_bf16_f32 v157, v104, v105
	ds_read_b64_tr_b16 v[66:67], v206 offset:33792
	ds_read_b64_tr_b16 v[68:69], v206 offset:34304
	s_waitcnt lgkmcnt(11)
	v_mfma_f32_32x32x16_bf16 v[114:129], v[190:193], v[158:161], v[114:129]
	v_add_f32_e32 v70, v108, v70
	v_add_f32_e32 v70, v109, v70
	v_add_f32_e32 v70, v110, v70
	v_add_f32_e32 v98, v111, v70
	v_cvt_pk_bf16_f32 v146, v106, v107
	v_cvt_pk_bf16_f32 v147, v108, v109
	ds_read_b64_tr_b16 v[70:71], v206 offset:37888
	ds_read_b64_tr_b16 v[72:73], v206 offset:38400
	s_waitcnt lgkmcnt(12)
	v_mfma_f32_32x32x16_bf16 v[50:65], v[78:81], v[158:161], v[50:65]
	v_add_f32_e32 v78, v112, v98
	v_add_f32_e32 v78, v113, v78
	v_add_f32_e32 v78, v82, v78
	v_add_f32_e32 v98, v83, v78
	v_cvt_pk_bf16_f32 v148, v110, v111
	v_cvt_pk_bf16_f32 v149, v112, v113
	ds_read_b64_tr_b16 v[78:79], v206 offset:34816
	ds_read_b64_tr_b16 v[80:81], v206 offset:35328
	s_waitcnt lgkmcnt(13)
	v_mfma_f32_32x32x16_bf16 v[114:129], v[182:185], v[150:153], v[114:129]
	v_add_f32_e32 v98, v84, v98
	v_add_f32_e32 v98, v85, v98
	v_add_f32_e32 v98, v86, v98
	v_add_f32_e32 v98, v87, v98
	v_cvt_pk_bf16_f32 v138, v82, v83
	v_cvt_pk_bf16_f32 v139, v84, v85
	ds_read_b64_tr_b16 v[82:83], v206 offset:38912
	ds_read_b64_tr_b16 v[84:85], v206 offset:39424
	s_waitcnt lgkmcnt(14)
	v_mfma_f32_32x32x16_bf16 v[50:65], v[178:181], v[150:153], v[50:65]
	v_add_f32_e32 v98, v88, v98
	v_add_f32_e32 v98, v89, v98
	v_add_f32_e32 v98, v90, v98
	v_add_f32_e32 v98, v91, v98
	v_cvt_pk_bf16_f32 v140, v86, v87
	v_cvt_pk_bf16_f32 v141, v88, v89
	ds_read_b64_tr_b16 v[86:87], v206 offset:35840
	ds_read_b64_tr_b16 v[88:89], v206 offset:36352
	s_waitcnt lgkmcnt(14)
	v_mfma_f32_32x32x16_bf16 v[114:129], v[174:177], v[142:145], v[114:129]
	v_add_f32_e32 v98, v92, v98
	v_add_f32_e32 v98, v93, v98
	v_add_f32_e32 v98, v94, v98
	v_add_f32_e32 v98, v95, v98
	v_cvt_pk_bf16_f32 v134, v90, v91
	v_cvt_pk_bf16_f32 v135, v92, v93
	ds_read_b64_tr_b16 v[90:91], v206 offset:39936
	ds_read_b64_tr_b16 v[92:93], v206 offset:40448
	v_mfma_f32_32x32x16_bf16 v[50:65], v[170:173], v[142:145], v[50:65]
	v_add_f32_e32 v98, v96, v98
	v_add_f32_e32 v98, v97, v98
	s_nop 0
	v_cvt_pk_bf16_f32 v136, v94, v95
	v_cvt_pk_bf16_f32 v137, v96, v97
	s_mov_b64 s[10:11], 0x1180000
	s_cmp_lg_u32 0, -1
	v_lshl_add_u64 v[94:95], v[196:197], 0, s[10:11]
	s_cselect_b32 s10, 0, 0
	s_add_i32 s10, s10, s18
	s_addk_i32 s10, 0x4000
	s_mov_b32 s11, m0
	s_mov_b32 m0, s10
	s_nop 0
	global_load_lds_dwordx4 v[94:95], off
	s_mov_b32 m0, s11
	s_mov_b64 s[10:11], 0x1080000
	v_lshl_add_u64 v[94:95], v[194:195], 0, s[10:11]
	s_mov_b32 s10, m0
	s_mov_b32 m0, s19
	s_nop 0
	global_load_lds_dwordx4 v[94:95], off
	s_mov_b32 m0, s10
	v_max_f32_e32 v94, v115, v114
	s_nop 1
	v_max3_f32 v95, v116, v117, v51
	v_max3_f32 v94, v94, v50, v52
	v_max3_f32 v94, v94, v53, v118
	v_max3_f32 v95, v95, v120, v121
	v_max3_f32 v94, v94, v119, v54
	v_max3_f32 v95, v95, v56, v57
	v_max3_f32 v94, v94, v55, v122
	v_max3_f32 v95, v95, v124, v125
	v_max3_f32 v94, v94, v123, v58
	v_max3_f32 v95, v95, v60, v61
	v_max3_f32 v94, v94, v59, v126
	v_max3_f32 v95, v95, v128, v129
	v_max3_f32 v94, v94, v127, v62
	v_max3_f32 v95, v95, v64, v65
	v_max3_f32 v94, v94, v63, v95
	v_mov_b32_e32 v95, v94
	s_nop 1
	v_permlane32_swap_b32_e32 v94, v95
	s_nop 1
	v_max_f32_e32 v94, v94, v95
	v_cmp_lt_f32_e32 vcc, s22, v94
	s_cmp_lg_u64 vcc, 0
	v_add_f32_e32 v209, v209, v98
	s_cselect_b64 s[10:11], -1, 0
	s_cbranch_vccnz .LBB0_976

.LBB0_953:
	ds_read_b64_tr_b16 v[166:167], v206 offset:40960
	ds_read_b64_tr_b16 v[168:169], v206 offset:41472
	s_waitcnt lgkmcnt(9)
	v_mfma_f32_32x32x16_bf16 v[98:113], v[74:77], v[162:165], v[34:49]
	v_add_f32_e32 v66, v114, v115
	v_add_f32_e32 v66, v116, v66
	v_add_f32_e32 v66, v117, v66
	v_add_f32_e32 v66, v118, v66
	v_add_f32_e32 v66, v119, v66
	v_cvt_pk_bf16_f32 v154, v114, v115
	v_cvt_pk_bf16_f32 v155, v116, v117
	ds_read_b64_tr_b16 v[90:91], v206 offset:45056
	ds_read_b64_tr_b16 v[92:93], v206 offset:45568
	v_add_f32_e32 v66, v120, v66
	v_add_f32_e32 v66, v121, v66
	v_add_f32_e32 v66, v122, v66
	v_add_f32_e32 v86, v123, v66
	s_waitcnt lgkmcnt(10)
	v_mfma_f32_32x32x16_bf16 v[66:81], v[186:189], v[162:165], v[34:49]
	v_cvt_pk_bf16_f32 v156, v118, v119
	v_cvt_pk_bf16_f32 v157, v120, v121
	ds_read_b64_tr_b16 v[82:83], v206 offset:41984
	ds_read_b64_tr_b16 v[84:85], v206 offset:42496
	s_waitcnt lgkmcnt(11)
	v_mfma_f32_32x32x16_bf16 v[98:113], v[190:193], v[158:161], v[98:113]
	v_add_f32_e32 v86, v124, v86
	v_add_f32_e32 v86, v125, v86
	v_add_f32_e32 v86, v126, v86
	v_add_f32_e32 v114, v127, v86
	v_cvt_pk_bf16_f32 v146, v122, v123
	v_cvt_pk_bf16_f32 v147, v124, v125
	ds_read_b64_tr_b16 v[86:87], v206 offset:46080
	ds_read_b64_tr_b16 v[88:89], v206 offset:46592
	s_waitcnt lgkmcnt(12)
	v_mfma_f32_32x32x16_bf16 v[66:81], v[94:97], v[158:161], v[66:81]
	v_add_f32_e32 v94, v128, v114
	v_add_f32_e32 v94, v129, v94
	v_add_f32_e32 v94, v50, v94
	v_add_f32_e32 v114, v51, v94
	v_cvt_pk_bf16_f32 v148, v126, v127
	v_cvt_pk_bf16_f32 v149, v128, v129
	ds_read_b64_tr_b16 v[94:95], v206 offset:43008
	ds_read_b64_tr_b16 v[96:97], v206 offset:43520
	s_waitcnt lgkmcnt(13)
	v_mfma_f32_32x32x16_bf16 v[98:113], v[182:185], v[150:153], v[98:113]
	v_add_f32_e32 v114, v52, v114
	v_add_f32_e32 v114, v53, v114
	v_add_f32_e32 v114, v54, v114
	v_add_f32_e32 v114, v55, v114
	v_cvt_pk_bf16_f32 v138, v50, v51
	v_cvt_pk_bf16_f32 v139, v52, v53
	ds_read_b64_tr_b16 v[50:51], v206 offset:47104
	ds_read_b64_tr_b16 v[52:53], v206 offset:47616
	s_waitcnt lgkmcnt(14)
	v_mfma_f32_32x32x16_bf16 v[66:81], v[178:181], v[150:153], v[66:81]
	v_add_f32_e32 v114, v56, v114
	v_add_f32_e32 v114, v57, v114
	v_add_f32_e32 v114, v58, v114
	v_add_f32_e32 v114, v59, v114
	v_cvt_pk_bf16_f32 v140, v54, v55
	v_cvt_pk_bf16_f32 v141, v56, v57
	ds_read_b64_tr_b16 v[54:55], v206 offset:44032
	ds_read_b64_tr_b16 v[56:57], v206 offset:44544
	s_waitcnt lgkmcnt(14)
	v_mfma_f32_32x32x16_bf16 v[98:113], v[174:177], v[142:145], v[98:113]
	v_add_f32_e32 v114, v60, v114
	v_add_f32_e32 v114, v61, v114
	v_add_f32_e32 v114, v62, v114
	v_add_f32_e32 v114, v63, v114
	v_cvt_pk_bf16_f32 v134, v58, v59
	v_cvt_pk_bf16_f32 v135, v60, v61
	ds_read_b64_tr_b16 v[58:59], v206 offset:48128
	ds_read_b64_tr_b16 v[60:61], v206 offset:48640
	v_mfma_f32_32x32x16_bf16 v[66:81], v[170:173], v[142:145], v[66:81]
	v_add_f32_e32 v114, v64, v114
	v_add_f32_e32 v114, v65, v114
	s_nop 0
	v_cvt_pk_bf16_f32 v136, v62, v63
	v_cvt_pk_bf16_f32 v137, v64, v65
	s_mov_b64 s[10:11], 0x1100000
	s_cmp_lg_u32 0, -1
	v_lshl_add_u64 v[62:63], v[194:195], 0, s[10:11]
	s_cselect_b32 s10, 0, 0
	s_add_i32 s10, s10, s18
	s_add_i32 s10, s10, 0x8000
	s_mov_b32 s11, m0
	s_mov_b32 m0, s10
	s_nop 0
	global_load_lds_dwordx4 v[62:63], off
	s_mov_b32 m0, s11
	v_max_f32_e32 v62, v99, v98
	s_nop 1
	v_max3_f32 v63, v100, v101, v67
	v_max3_f32 v62, v62, v66, v68
	v_max3_f32 v62, v62, v69, v102
	v_max3_f32 v63, v63, v104, v105
	v_max3_f32 v62, v62, v103, v70
	v_max3_f32 v63, v63, v72, v73
	v_max3_f32 v62, v62, v71, v106
	v_max3_f32 v63, v63, v108, v109
	v_max3_f32 v62, v62, v107, v74
	v_max3_f32 v63, v63, v76, v77
	v_max3_f32 v62, v62, v75, v110
	v_max3_f32 v63, v63, v112, v113
	v_max3_f32 v62, v62, v111, v78
	v_max3_f32 v63, v63, v80, v81
	v_max3_f32 v62, v62, v79, v63
	v_mov_b32_e32 v63, v62
	s_nop 1
	v_permlane32_swap_b32_e32 v62, v63
	s_nop 1
	v_max_f32_e32 v62, v62, v63
	v_cmp_lt_f32_e32 vcc, s22, v62
	s_cmp_lg_u64 vcc, 0
	v_add_f32_e32 v186, v209, v114
	s_cselect_b64 s[10:11], -1, 0
	s_cbranch_vccnz .LBB0_979

.LBB0_956:
	ds_read_b64_tr_b16 v[118:119], v206 offset:24576
	ds_read_b64_tr_b16 v[120:121], v206 offset:25088
	s_waitcnt lgkmcnt(9)
	v_mfma_f32_32x32x16_bf16 v[82:97], v[62:65], v[162:165], v[34:49]
	v_add_f32_e32 v50, v98, v99
	v_add_f32_e32 v50, v100, v50
	v_add_f32_e32 v50, v101, v50
	v_add_f32_e32 v50, v102, v50
	v_add_f32_e32 v50, v103, v50
	v_cvt_pk_bf16_f32 v154, v98, v99
	v_cvt_pk_bf16_f32 v155, v100, v101
	ds_read_b64_tr_b16 v[114:115], v206 offset:28672
	ds_read_b64_tr_b16 v[116:117], v206 offset:29184
	v_add_f32_e32 v50, v104, v50
	v_add_f32_e32 v50, v105, v50
	v_add_f32_e32 v50, v106, v50
	v_add_f32_e32 v134, v107, v50
	s_waitcnt lgkmcnt(10)
	v_mfma_f32_32x32x16_bf16 v[50:65], v[178:181], v[162:165], v[34:49]
	v_cvt_pk_bf16_f32 v156, v102, v103
	v_cvt_pk_bf16_f32 v157, v104, v105
	ds_read_b64_tr_b16 v[98:99], v206 offset:25600
	ds_read_b64_tr_b16 v[100:101], v206 offset:26112
	s_waitcnt lgkmcnt(11)
	v_mfma_f32_32x32x16_bf16 v[82:97], v[182:185], v[158:161], v[82:97]
	v_add_f32_e32 v102, v108, v134
	v_add_f32_e32 v102, v109, v102
	v_add_f32_e32 v102, v110, v102
	v_add_f32_e32 v134, v111, v102
	v_cvt_pk_bf16_f32 v146, v106, v107
	v_cvt_pk_bf16_f32 v147, v108, v109
	ds_read_b64_tr_b16 v[102:103], v206 offset:29696
	ds_read_b64_tr_b16 v[104:105], v206 offset:30208
	s_waitcnt lgkmcnt(12)
	v_mfma_f32_32x32x16_bf16 v[50:65], v[174:177], v[158:161], v[50:65]
	v_add_f32_e32 v106, v112, v134
	v_add_f32_e32 v106, v113, v106
	v_add_f32_e32 v106, v66, v106
	v_add_f32_e32 v134, v67, v106
	v_cvt_pk_bf16_f32 v148, v110, v111
	v_cvt_pk_bf16_f32 v149, v112, v113
	ds_read_b64_tr_b16 v[106:107], v206 offset:26624
	ds_read_b64_tr_b16 v[108:109], v206 offset:27136
	s_waitcnt lgkmcnt(13)
	v_mfma_f32_32x32x16_bf16 v[82:97], v[170:173], v[150:153], v[82:97]
	v_add_f32_e32 v110, v68, v134
	v_add_f32_e32 v110, v69, v110
	v_add_f32_e32 v110, v70, v110
	v_add_f32_e32 v110, v71, v110
	v_cvt_pk_bf16_f32 v138, v66, v67
	v_cvt_pk_bf16_f32 v139, v68, v69
	ds_read_b64_tr_b16 v[66:67], v206 offset:30720
	ds_read_b64_tr_b16 v[68:69], v206 offset:31232
	s_waitcnt lgkmcnt(14)
	v_mfma_f32_32x32x16_bf16 v[50:65], v[166:169], v[150:153], v[50:65]
	v_add_f32_e32 v110, v72, v110
	v_add_f32_e32 v110, v73, v110
	v_add_f32_e32 v110, v74, v110
	v_add_f32_e32 v110, v75, v110
	v_cvt_pk_bf16_f32 v140, v70, v71
	v_cvt_pk_bf16_f32 v141, v72, v73
	ds_read_b64_tr_b16 v[70:71], v206 offset:27648
	ds_read_b64_tr_b16 v[72:73], v206 offset:28160
	s_waitcnt lgkmcnt(14)
	v_mfma_f32_32x32x16_bf16 v[82:97], v[126:129], v[142:145], v[82:97]
	v_add_f32_e32 v110, v76, v110
	v_add_f32_e32 v110, v77, v110
	v_add_f32_e32 v110, v78, v110
	v_add_f32_e32 v110, v79, v110
	v_cvt_pk_bf16_f32 v134, v74, v75
	v_cvt_pk_bf16_f32 v135, v76, v77
	ds_read_b64_tr_b16 v[74:75], v206 offset:31744
	ds_read_b64_tr_b16 v[76:77], v206 offset:32256
	v_mfma_f32_32x32x16_bf16 v[50:65], v[122:125], v[142:145], v[50:65]
	v_add_f32_e32 v110, v80, v110
	v_add_f32_e32 v110, v81, v110
	s_nop 0
	v_cvt_pk_bf16_f32 v136, v78, v79
	v_cvt_pk_bf16_f32 v137, v80, v81
	s_mov_b64 s[10:11], 0x1180000
	v_lshl_add_u64 v[78:79], v[194:195], 0, s[10:11]
	s_mov_b32 s10, m0
	s_mov_b32 m0, s26
	s_nop 0
	global_load_lds_dwordx4 v[78:79], off
	s_mov_b32 m0, s10
	v_max_f32_e32 v78, v83, v82
	s_nop 3
	v_max3_f32 v79, v84, v85, v51
	v_max3_f32 v78, v78, v50, v52
	v_max3_f32 v78, v78, v53, v86
	v_max3_f32 v79, v79, v88, v89
	v_max3_f32 v78, v78, v87, v54
	v_max3_f32 v79, v79, v56, v57
	v_max3_f32 v78, v78, v55, v90
	v_max3_f32 v79, v79, v92, v93
	v_max3_f32 v78, v78, v91, v58
	v_max3_f32 v79, v79, v60, v61
	v_max3_f32 v78, v78, v59, v94
	v_max3_f32 v79, v79, v96, v97
	v_max3_f32 v78, v78, v95, v62
	v_max3_f32 v79, v79, v64, v65
	v_max3_f32 v78, v78, v63, v79
	v_mov_b32_e32 v79, v78
	s_nop 1
	v_permlane32_swap_b32_e32 v78, v79
	s_nop 1
	v_max_f32_e32 v78, v78, v79
	v_cmp_lt_f32_e32 vcc, s22, v78
	s_cmp_lg_u64 vcc, 0
	v_add_f32_e32 v174, v186, v110
	s_cselect_b64 s[10:11], -1, 0
	s_cbranch_vccnz .LBB0_982

.LBB0_959:
	ds_read_b64_tr_b16 v[98:99], v206 offset:32768
	ds_read_b64_tr_b16 v[100:101], v206 offset:33280
	v_add_f32_e32 v66, v82, v83
	v_add_f32_e32 v66, v84, v66
	v_add_f32_e32 v66, v85, v66
	v_add_f32_e32 v66, v86, v66
	v_add_f32_e32 v106, v87, v66
	s_waitcnt lgkmcnt(9)
	v_mfma_f32_32x32x16_bf16 v[66:81], v[170:173], v[162:165], v[34:49]
	v_cvt_pk_bf16_f32 v154, v82, v83
	v_cvt_pk_bf16_f32 v155, v84, v85
	ds_read_b64_tr_b16 v[82:83], v206 offset:36864
	ds_read_b64_tr_b16 v[84:85], v206 offset:37376
	s_waitcnt lgkmcnt(10)
	v_mfma_f32_32x32x16_bf16 v[34:49], v[166:169], v[162:165], v[34:49]
	v_add_f32_e32 v106, v88, v106
	v_add_f32_e32 v106, v89, v106
	v_add_f32_e32 v106, v90, v106
	v_add_f32_e32 v106, v91, v106
	v_cvt_pk_bf16_f32 v156, v86, v87
	v_cvt_pk_bf16_f32 v157, v88, v89
	ds_read_b64_tr_b16 v[86:87], v206 offset:33792
	ds_read_b64_tr_b16 v[88:89], v206 offset:34304
	s_waitcnt lgkmcnt(11)
	v_mfma_f32_32x32x16_bf16 v[66:81], v[126:129], v[158:161], v[66:81]
	v_add_f32_e32 v106, v92, v106
	v_add_f32_e32 v106, v93, v106
	v_add_f32_e32 v106, v94, v106
	v_add_f32_e32 v106, v95, v106
	v_cvt_pk_bf16_f32 v146, v90, v91
	v_cvt_pk_bf16_f32 v147, v92, v93
	ds_read_b64_tr_b16 v[90:91], v206 offset:37888
	ds_read_b64_tr_b16 v[92:93], v206 offset:38400
	s_waitcnt lgkmcnt(12)
	v_mfma_f32_32x32x16_bf16 v[34:49], v[122:125], v[158:161], v[34:49]
	v_add_f32_e32 v106, v96, v106
	v_add_f32_e32 v106, v97, v106
	v_add_f32_e32 v106, v50, v106
	v_add_f32_e32 v106, v51, v106
	v_cvt_pk_bf16_f32 v148, v94, v95
	v_cvt_pk_bf16_f32 v149, v96, v97
	ds_read_b64_tr_b16 v[94:95], v206 offset:34816
	ds_read_b64_tr_b16 v[96:97], v206 offset:35328
	s_waitcnt lgkmcnt(13)
	v_mfma_f32_32x32x16_bf16 v[66:81], v[102:105], v[150:153], v[66:81]
	v_add_f32_e32 v102, v52, v106
	v_add_f32_e32 v102, v53, v102
	v_add_f32_e32 v102, v54, v102
	v_add_f32_e32 v106, v55, v102
	v_cvt_pk_bf16_f32 v138, v50, v51
	v_cvt_pk_bf16_f32 v139, v52, v53
	ds_read_b64_tr_b16 v[102:103], v206 offset:38912
	ds_read_b64_tr_b16 v[104:105], v206 offset:39424
	s_waitcnt lgkmcnt(14)
	v_mfma_f32_32x32x16_bf16 v[34:49], v[118:121], v[150:153], v[34:49]
	v_add_f32_e32 v50, v56, v106
	v_add_f32_e32 v50, v57, v50
	v_add_f32_e32 v50, v58, v50
	v_add_f32_e32 v50, v59, v50
	v_cvt_pk_bf16_f32 v140, v54, v55
	v_cvt_pk_bf16_f32 v141, v56, v57
	ds_read_b64_tr_b16 v[106:107], v206 offset:35840
	ds_read_b64_tr_b16 v[108:109], v206 offset:36352
	s_waitcnt lgkmcnt(14)
	v_mfma_f32_32x32x16_bf16 v[66:81], v[114:117], v[142:145], v[66:81]
	v_add_f32_e32 v50, v60, v50
	v_add_f32_e32 v50, v61, v50
	v_add_f32_e32 v50, v62, v50
	v_add_f32_e32 v50, v63, v50
	v_cvt_pk_bf16_f32 v134, v58, v59
	v_cvt_pk_bf16_f32 v135, v60, v61
	ds_read_b64_tr_b16 v[114:115], v206 offset:39936
	ds_read_b64_tr_b16 v[116:117], v206 offset:40448
	v_mfma_f32_32x32x16_bf16 v[34:49], v[110:113], v[142:145], v[34:49]
	v_add_f32_e32 v50, v64, v50
	v_add_f32_e32 v50, v65, v50
	s_nop 0
	v_cvt_pk_bf16_f32 v136, v62, v63
	v_cvt_pk_bf16_f32 v137, v64, v65
	v_max_f32_e32 v51, v67, v66
	s_nop 5
	v_max3_f32 v52, v68, v69, v35
	v_max3_f32 v51, v51, v34, v36
	v_max3_f32 v51, v51, v37, v70
	v_max3_f32 v52, v52, v72, v73
	v_max3_f32 v51, v51, v71, v38
	v_max3_f32 v52, v52, v40, v41
	v_max3_f32 v51, v51, v39, v74
	v_max3_f32 v52, v52, v76, v77
	v_max3_f32 v51, v51, v75, v42
	v_max3_f32 v52, v52, v44, v45
	v_max3_f32 v51, v51, v43, v78
	v_max3_f32 v52, v52, v80, v81
	v_max3_f32 v51, v51, v79, v46
	v_max3_f32 v52, v52, v48, v49
	v_add_f32_e32 v110, v174, v50
	v_max3_f32 v50, v51, v47, v52
	v_mov_b32_e32 v51, v50
	s_nop 1
	v_permlane32_swap_b32_e32 v50, v51
	s_nop 1
	v_max_f32_e32 v50, v50, v51
	v_cmp_lt_f32_e32 vcc, s22, v50
	s_cmp_lg_u64 vcc, 0
	s_cselect_b64 s[10:11], -1, 0
	s_cbranch_vccnz .LBB0_985

.LBB0_1233:
	v_add_f32_e32 v15, v237, v14
	v_max_f32_e32 v14, v113, v112
	s_nop 1
	v_max3_f32 v76, v114, v115, v97
	v_max3_f32 v14, v14, v96, v98
	v_max3_f32 v14, v14, v99, v116
	v_max3_f32 v76, v76, v118, v119
	v_max3_f32 v14, v14, v117, v100
	v_max3_f32 v76, v76, v102, v103
	v_max3_f32 v14, v14, v101, v120
	v_max3_f32 v76, v76, v122, v123
	v_max3_f32 v14, v14, v121, v104
	v_max3_f32 v76, v76, v106, v107
	v_max3_f32 v14, v14, v105, v124
	v_max3_f32 v76, v76, v126, v127
	v_max3_f32 v14, v14, v125, v108
	v_max3_f32 v76, v76, v110, v111
	v_max3_f32 v14, v14, v109, v76
	v_mov_b32_e32 v76, v14
	s_nop 1
	v_permlane32_swap_b32_e32 v14, v76
	s_nop 1
	v_max_f32_e32 v14, v14, v76
	v_cmp_lt_f32_e32 vcc, s22, v14
	s_cmp_lg_u64 vcc, 0
	s_cselect_b64 s[16:17], -1, 0
	s_cbranch_vccnz .LBB0_1243

.LBB0_1236:
	s_add_i32 s13, s21, 0x2000
	s_cmpk_lg_i32 s21, 0x4000
	s_cselect_b32 s13, s13, 0
	v_add_u32_e32 v194, s57, v235
	ds_read_b64_tr_b16 v[166:167], v194 offset:24576
	ds_read_b64_tr_b16 v[168:169], v194 offset:25088
	s_waitcnt lgkmcnt(9)
	v_mfma_f32_32x32x16_bf16 v[80:95], v[76:79], v[162:165], v[48:63]
	v_add_f32_e32 v2, v112, v113
	v_add_f32_e32 v2, v114, v2
	v_add_f32_e32 v2, v115, v2
	v_add_f32_e32 v2, v116, v2
	v_add_f32_e32 v2, v117, v2
	v_cvt_pk_bf16_f32 v146, v112, v113
	v_cvt_pk_bf16_f32 v147, v114, v115
	ds_read_b64_tr_b16 v[112:113], v194 offset:28672
	ds_read_b64_tr_b16 v[114:115], v194 offset:29184
	s_waitcnt lgkmcnt(10)
	v_mfma_f32_32x32x16_bf16 v[64:79], v[186:189], v[162:165], v[48:63]
	v_add_f32_e32 v2, v118, v2
	v_add_f32_e32 v2, v119, v2
	v_add_f32_e32 v2, v120, v2
	v_add_f32_e32 v6, v121, v2
	v_cvt_pk_bf16_f32 v148, v116, v117
	v_cvt_pk_bf16_f32 v149, v118, v119
	ds_read_b64_tr_b16 v[2:3], v194 offset:25600
	ds_read_b64_tr_b16 v[4:5], v194 offset:26112
	s_waitcnt lgkmcnt(11)
	v_mfma_f32_32x32x16_bf16 v[80:95], v[190:193], v[158:161], v[80:95]
	v_add_f32_e32 v6, v122, v6
	v_add_f32_e32 v6, v123, v6
	v_add_f32_e32 v6, v124, v6
	v_add_f32_e32 v116, v125, v6
	v_cvt_pk_bf16_f32 v142, v120, v121
	v_cvt_pk_bf16_f32 v143, v122, v123
	ds_read_b64_tr_b16 v[6:7], v194 offset:29696
	ds_read_b64_tr_b16 v[8:9], v194 offset:30208
	s_waitcnt lgkmcnt(12)
	v_mfma_f32_32x32x16_bf16 v[64:79], v[10:13], v[158:161], v[64:79]
	v_add_f32_e32 v10, v126, v116
	v_add_f32_e32 v10, v127, v10
	v_add_f32_e32 v10, v96, v10
	v_add_f32_e32 v116, v97, v10
	v_cvt_pk_bf16_f32 v144, v124, v125
	v_cvt_pk_bf16_f32 v145, v126, v127
	ds_read_b64_tr_b16 v[10:11], v194 offset:26624
	ds_read_b64_tr_b16 v[12:13], v194 offset:27136
	s_waitcnt lgkmcnt(13)
	v_mfma_f32_32x32x16_bf16 v[80:95], v[182:185], v[154:157], v[80:95]
	v_add_f32_e32 v116, v98, v116
	v_add_f32_e32 v116, v99, v116
	v_add_f32_e32 v116, v100, v116
	v_add_f32_e32 v116, v101, v116
	v_cvt_pk_bf16_f32 v138, v96, v97
	v_cvt_pk_bf16_f32 v139, v98, v99
	ds_read_b64_tr_b16 v[96:97], v194 offset:30720
	ds_read_b64_tr_b16 v[98:99], v194 offset:31232
	s_waitcnt lgkmcnt(14)
	v_mfma_f32_32x32x16_bf16 v[64:79], v[178:181], v[154:157], v[64:79]
	v_add_f32_e32 v116, v102, v116
	v_add_f32_e32 v116, v103, v116
	v_add_f32_e32 v116, v104, v116
	v_add_f32_e32 v116, v105, v116
	v_cvt_pk_bf16_f32 v140, v100, v101
	v_cvt_pk_bf16_f32 v141, v102, v103
	ds_read_b64_tr_b16 v[100:101], v194 offset:27648
	ds_read_b64_tr_b16 v[102:103], v194 offset:28160
	s_waitcnt lgkmcnt(14)
	v_mfma_f32_32x32x16_bf16 v[80:95], v[174:177], v[150:153], v[80:95]
	v_add_f32_e32 v116, v106, v116
	v_add_f32_e32 v116, v107, v116
	v_add_f32_e32 v116, v108, v116
	v_add_f32_e32 v116, v109, v116
	v_cvt_pk_bf16_f32 v134, v104, v105
	v_cvt_pk_bf16_f32 v135, v106, v107
	ds_read_b64_tr_b16 v[104:105], v194 offset:31744
	ds_read_b64_tr_b16 v[106:107], v194 offset:32256
	v_mfma_f32_32x32x16_bf16 v[64:79], v[170:173], v[150:153], v[64:79]
	v_add_f32_e32 v116, v110, v116
	v_add_f32_e32 v116, v111, v116
	s_nop 0
	v_cvt_pk_bf16_f32 v136, v108, v109
	v_cvt_pk_bf16_f32 v137, v110, v111
	s_add_i32 s16, s21, s90
	s_cmp_gt_u32 s64, 1
	s_mov_b32 s17, m0
	s_mov_b32 m0, s16
	s_nop 0
	global_load_lds_dwordx4 v[204:205], off
	s_mov_b32 m0, s17
	s_cselect_b32 s16, s12, 0
	s_add_i32 s16, s16, s56
	s_ashr_i32 s17, s16, 31
	s_lshl_b64 s[16:17], s[16:17], 13
	v_lshl_add_u64 v[108:109], v[128:129], 0, s[16:17]
	s_add_i32 s16, s13, s91
	s_mov_b32 s17, m0
	s_mov_b32 m0, s16
	s_nop 0
	global_load_lds_dwordx4 v[108:109], off
	s_mov_b32 m0, s17
	s_andn2_b64 vcc, exec, s[6:7]
	s_cbranch_vccnz .LBB0_1238
	v_add_u32_e32 v108, 0xfffffe3f, v0
	v_cmp_lt_u32_e32 vcc, s38, v108
	v_add_u32_e32 v108, 0xfffffe5f, v0
	s_nop 0
	v_cndmask_b32_e32 v80, v218, v80, vcc
	v_cmp_lt_u32_e32 vcc, s38, v108
	v_add_u32_e32 v108, 0xfffffe40, v0
	s_nop 0
	v_cndmask_b32_e32 v64, v218, v64, vcc
	v_cmp_lt_u32_e32 vcc, s38, v108
	v_add_u32_e32 v108, 0xfffffe60, v0
	s_nop 0
	v_cndmask_b32_e32 v81, v218, v81, vcc
	v_cmp_lt_u32_e32 vcc, s38, v108
	v_add_u32_e32 v108, 0xfffffe41, v0
	s_nop 0
	v_cndmask_b32_e32 v65, v218, v65, vcc
	v_cmp_lt_u32_e32 vcc, s38, v108
	v_add_u32_e32 v108, 0xfffffe61, v0
	s_nop 0
	v_cndmask_b32_e32 v82, v218, v82, vcc
	v_cmp_lt_u32_e32 vcc, s38, v108
	v_add_u32_e32 v108, 0xfffffe42, v0
	s_nop 0
	v_cndmask_b32_e32 v66, v218, v66, vcc
	v_cmp_lt_u32_e32 vcc, s38, v108
	v_add_u32_e32 v108, 0xfffffe62, v0
	s_nop 0
	v_cndmask_b32_e32 v83, v218, v83, vcc
	v_cmp_lt_u32_e32 vcc, s38, v108
	v_add_u32_e32 v108, 0xfffffe47, v0
	s_nop 0
	v_cndmask_b32_e32 v67, v218, v67, vcc
	v_cmp_lt_u32_e32 vcc, s38, v108
	v_add_u32_e32 v108, 0xfffffe67, v0
	s_nop 0
	v_cndmask_b32_e32 v84, v218, v84, vcc
	v_cmp_lt_u32_e32 vcc, s38, v108
	v_add_u32_e32 v108, 0xfffffe48, v0
	s_nop 0
	v_cndmask_b32_e32 v68, v218, v68, vcc
	v_cmp_lt_u32_e32 vcc, s38, v108
	v_add_u32_e32 v108, 0xfffffe68, v0
	s_nop 0
	v_cndmask_b32_e32 v85, v218, v85, vcc
	v_cmp_lt_u32_e32 vcc, s38, v108
	v_add_u32_e32 v108, 0xfffffe49, v0
	s_nop 0
	v_cndmask_b32_e32 v69, v218, v69, vcc
	v_cmp_lt_u32_e32 vcc, s38, v108
	v_add_u32_e32 v108, 0xfffffe69, v0
	s_nop 0
	v_cndmask_b32_e32 v86, v218, v86, vcc
	v_cmp_lt_u32_e32 vcc, s38, v108
	v_add_u32_e32 v108, 0xfffffe4a, v0
	s_nop 0
	v_cndmask_b32_e32 v70, v218, v70, vcc
	v_cmp_lt_u32_e32 vcc, s38, v108
	v_add_u32_e32 v108, 0xfffffe6a, v0
	s_nop 0
	v_cndmask_b32_e32 v87, v218, v87, vcc
	v_cmp_lt_u32_e32 vcc, s38, v108
	v_add_u32_e32 v108, 0xfffffe4f, v0
	s_nop 0
	v_cndmask_b32_e32 v71, v218, v71, vcc
	v_cmp_lt_u32_e32 vcc, s38, v108
	v_add_u32_e32 v108, 0xfffffe6f, v0
	s_nop 0
	v_cndmask_b32_e32 v88, v218, v88, vcc
	v_cmp_lt_u32_e32 vcc, s38, v108
	v_add_u32_e32 v108, 0xfffffe50, v0
	s_nop 0
	v_cndmask_b32_e32 v72, v218, v72, vcc
	v_cmp_lt_u32_e32 vcc, s38, v108
	v_add_u32_e32 v108, 0xfffffe70, v0
	s_nop 0
	v_cndmask_b32_e32 v89, v218, v89, vcc
	v_cmp_lt_u32_e32 vcc, s38, v108
	v_add_u32_e32 v108, 0xfffffe51, v0
	s_nop 0
	v_cndmask_b32_e32 v73, v218, v73, vcc
	v_cmp_lt_u32_e32 vcc, s38, v108
	v_add_u32_e32 v108, 0xfffffe71, v0
	s_nop 0
	v_cndmask_b32_e32 v90, v218, v90, vcc
	v_cmp_lt_u32_e32 vcc, s38, v108
	v_add_u32_e32 v108, 0xfffffe52, v0
	s_nop 0
	v_cndmask_b32_e32 v74, v218, v74, vcc
	v_cmp_lt_u32_e32 vcc, s38, v108
	v_add_u32_e32 v108, 0xfffffe72, v0
	s_nop 0
	v_cndmask_b32_e32 v91, v218, v91, vcc
	v_cmp_lt_u32_e32 vcc, s38, v108
	v_add_u32_e32 v108, 0xfffffe57, v0
	s_nop 0
	v_cndmask_b32_e32 v75, v218, v75, vcc
	v_cmp_lt_u32_e32 vcc, s38, v108
	v_add_u32_e32 v108, 0xfffffe77, v0
	s_nop 0
	v_cndmask_b32_e32 v92, v218, v92, vcc
	v_cmp_lt_u32_e32 vcc, s38, v108
	v_add_u32_e32 v108, 0xfffffe58, v0
	s_nop 0
	v_cndmask_b32_e32 v76, v218, v76, vcc
	v_cmp_lt_u32_e32 vcc, s38, v108
	v_add_u32_e32 v108, 0xfffffe78, v0
	s_nop 0
	v_cndmask_b32_e32 v93, v218, v93, vcc
	v_cmp_lt_u32_e32 vcc, s38, v108
	v_add_u32_e32 v108, 0xfffffe59, v0
	s_nop 0
	v_cndmask_b32_e32 v77, v218, v77, vcc
	v_cmp_lt_u32_e32 vcc, s38, v108
	v_add_u32_e32 v108, 0xfffffe79, v0
	s_nop 0
	v_cndmask_b32_e32 v94, v218, v94, vcc
	v_cmp_lt_u32_e32 vcc, s38, v108
	v_add_u32_e32 v108, 0xfffffe5a, v0
	v_add_u32_e32 v0, 0xfffffe7a, v0
	v_cndmask_b32_e32 v78, v218, v78, vcc
	v_cmp_lt_u32_e32 vcc, s38, v108
	s_nop 1
	v_cndmask_b32_e32 v95, v218, v95, vcc
	v_cmp_lt_u32_e32 vcc, s38, v0
	s_nop 1
	v_cndmask_b32_e32 v79, v218, v79, vcc
.LBB0_1238:
	v_add_f32_e32 v237, v15, v116
	v_max_f32_e32 v0, v81, v80
	s_nop 1
	v_max3_f32 v15, v82, v83, v65
	v_max3_f32 v0, v0, v64, v66
	v_max3_f32 v0, v0, v67, v84
	v_max3_f32 v15, v15, v86, v87
	v_max3_f32 v0, v0, v85, v68
	v_max3_f32 v15, v15, v70, v71
	v_max3_f32 v0, v0, v69, v88
	v_max3_f32 v15, v15, v90, v91
	v_max3_f32 v0, v0, v89, v72
	v_max3_f32 v15, v15, v74, v75
	v_max3_f32 v0, v0, v73, v92
	v_max3_f32 v15, v15, v94, v95
	v_max3_f32 v0, v0, v93, v76
	v_max3_f32 v15, v15, v78, v79
	v_max3_f32 v0, v0, v77, v15
	v_mov_b32_e32 v15, v0
	s_nop 1
	v_permlane32_swap_b32_e32 v0, v15
	s_nop 1
	v_max_f32_e32 v0, v0, v15
	v_cmp_lt_f32_e32 vcc, s22, v0
	s_cmp_lg_u64 vcc, 0
	s_cselect_b64 s[6:7], -1, 0
	s_cbranch_vccnz .LBB0_1246

.LBB0_1252:
	v_add_u32_e32 v202, s21, v235
	ds_read_b64_tr_b16 v[198:199], v202 offset:24576
	ds_read_b64_tr_b16 v[200:201], v202 offset:25088
	s_waitcnt lgkmcnt(9)
	v_mfma_f32_32x32x16_bf16 v[112:127], v[194:197], v[162:165], v[48:63]
	v_add_f32_e32 v2, v80, v81
	v_add_f32_e32 v2, v82, v2
	v_add_f32_e32 v2, v83, v2
	v_add_f32_e32 v2, v84, v2
	v_add_f32_e32 v2, v85, v2
	v_cvt_pk_bf16_f32 v146, v80, v81
	v_cvt_pk_bf16_f32 v147, v82, v83
	ds_read_b64_tr_b16 v[80:81], v202 offset:28672
	ds_read_b64_tr_b16 v[82:83], v202 offset:29184
	s_waitcnt lgkmcnt(10)
	v_mfma_f32_32x32x16_bf16 v[96:111], v[190:193], v[162:165], v[48:63]
	v_add_f32_e32 v2, v86, v2
	v_add_f32_e32 v2, v87, v2
	v_add_f32_e32 v2, v88, v2
	v_add_f32_e32 v6, v89, v2
	v_cvt_pk_bf16_f32 v148, v84, v85
	v_cvt_pk_bf16_f32 v149, v86, v87
	ds_read_b64_tr_b16 v[2:3], v202 offset:25600
	ds_read_b64_tr_b16 v[4:5], v202 offset:26112
	s_waitcnt lgkmcnt(11)
	v_mfma_f32_32x32x16_bf16 v[112:127], v[186:189], v[158:161], v[112:127]
	v_add_f32_e32 v6, v90, v6
	v_add_f32_e32 v6, v91, v6
	v_add_f32_e32 v6, v92, v6
	v_add_f32_e32 v10, v93, v6
	v_cvt_pk_bf16_f32 v142, v88, v89
	v_cvt_pk_bf16_f32 v143, v90, v91
	ds_read_b64_tr_b16 v[6:7], v202 offset:29696
	ds_read_b64_tr_b16 v[8:9], v202 offset:30208
	s_waitcnt lgkmcnt(12)
	v_mfma_f32_32x32x16_bf16 v[96:111], v[182:185], v[158:161], v[96:111]
	v_add_f32_e32 v10, v94, v10
	v_add_f32_e32 v10, v95, v10
	v_add_f32_e32 v10, v64, v10
	v_add_f32_e32 v84, v65, v10
	v_cvt_pk_bf16_f32 v144, v92, v93
	v_cvt_pk_bf16_f32 v145, v94, v95
	ds_read_b64_tr_b16 v[10:11], v202 offset:26624
	ds_read_b64_tr_b16 v[12:13], v202 offset:27136
	s_waitcnt lgkmcnt(13)
	v_mfma_f32_32x32x16_bf16 v[112:127], v[178:181], v[154:157], v[112:127]
	v_add_f32_e32 v84, v66, v84
	v_add_f32_e32 v84, v67, v84
	v_add_f32_e32 v84, v68, v84
	v_add_f32_e32 v84, v69, v84
	v_cvt_pk_bf16_f32 v138, v64, v65
	v_cvt_pk_bf16_f32 v139, v66, v67
	ds_read_b64_tr_b16 v[64:65], v202 offset:30720
	ds_read_b64_tr_b16 v[66:67], v202 offset:31232
	s_waitcnt lgkmcnt(14)
	v_mfma_f32_32x32x16_bf16 v[96:111], v[174:177], v[154:157], v[96:111]
	v_add_f32_e32 v84, v70, v84
	v_add_f32_e32 v84, v71, v84
	v_add_f32_e32 v84, v72, v84
	v_add_f32_e32 v84, v73, v84
	v_cvt_pk_bf16_f32 v140, v68, v69
	v_cvt_pk_bf16_f32 v141, v70, v71
	ds_read_b64_tr_b16 v[68:69], v202 offset:27648
	ds_read_b64_tr_b16 v[70:71], v202 offset:28160
	s_waitcnt lgkmcnt(14)
	v_mfma_f32_32x32x16_bf16 v[112:127], v[170:173], v[150:153], v[112:127]
	v_add_f32_e32 v84, v74, v84
	v_add_f32_e32 v84, v75, v84
	v_add_f32_e32 v84, v76, v84
	v_add_f32_e32 v84, v77, v84
	v_cvt_pk_bf16_f32 v134, v72, v73
	v_cvt_pk_bf16_f32 v135, v74, v75
	ds_read_b64_tr_b16 v[72:73], v202 offset:31744
	ds_read_b64_tr_b16 v[74:75], v202 offset:32256
	v_mfma_f32_32x32x16_bf16 v[96:111], v[166:169], v[150:153], v[96:111]
	v_add_f32_e32 v84, v78, v84
	v_add_f32_e32 v84, v79, v84
	s_nop 0
	v_cvt_pk_bf16_f32 v136, v76, v77
	v_cvt_pk_bf16_f32 v137, v78, v79
	s_add_i32 s6, s64, 3
	s_cmp_ge_i32 s6, s95
	s_cselect_b64 s[16:17], -1, 0
	s_and_b64 vcc, exec, s[16:17]
	s_cbranch_vccnz .LBB0_1254
	s_add_i32 s6, s13, s90
	s_mov_b32 s7, m0
	s_mov_b32 m0, s6
	s_nop 0
	global_load_lds_dwordx4 v[210:211], off
	s_mov_b32 m0, s7

.LBB0_1256:
	v_max_f32_e32 v76, v113, v112
	s_nop 1
	v_max3_f32 v77, v114, v115, v97
	v_max3_f32 v76, v76, v96, v98
	v_max3_f32 v76, v76, v99, v116
	v_max3_f32 v77, v77, v118, v119
	v_max3_f32 v76, v76, v117, v100
	v_max3_f32 v77, v77, v102, v103
	v_max3_f32 v76, v76, v101, v120
	v_max3_f32 v77, v77, v122, v123
	v_max3_f32 v76, v76, v121, v104
	v_max3_f32 v77, v77, v106, v107
	v_max3_f32 v76, v76, v105, v124
	v_max3_f32 v77, v77, v126, v127
	v_max3_f32 v76, v76, v125, v108
	v_max3_f32 v77, v77, v110, v111
	v_max3_f32 v76, v76, v109, v77
	v_mov_b32_e32 v77, v76
	s_nop 1
	v_permlane32_swap_b32_e32 v76, v77
	s_nop 1
	v_max_f32_e32 v76, v76, v77
	v_cmp_lt_f32_e32 vcc, s22, v76
	s_cmp_lg_u64 vcc, 0
	v_add_f32_e32 v237, v237, v84
	s_cselect_b64 s[18:19], -1, 0
	s_cbranch_vccnz .LBB0_1294

.LBB0_1261:
	v_add_u32_e32 v4, s13, v235
	ds_read_b64_tr_b16 v[206:207], v4 offset:24576
	ds_read_b64_tr_b16 v[208:209], v4 offset:25088
	s_waitcnt lgkmcnt(9)
	v_mfma_f32_32x32x16_bf16 v[80:95], v[194:197], v[162:165], v[48:63]
	v_add_f32_e32 v2, v112, v113
	v_add_f32_e32 v2, v114, v2
	v_add_f32_e32 v2, v115, v2
	v_add_f32_e32 v2, v116, v2
	v_add_f32_e32 v2, v117, v2
	v_cvt_pk_bf16_f32 v146, v112, v113
	v_cvt_pk_bf16_f32 v147, v114, v115
	ds_read_b64_tr_b16 v[202:203], v4 offset:28672
	ds_read_b64_tr_b16 v[204:205], v4 offset:29184
	s_waitcnt lgkmcnt(10)
	v_mfma_f32_32x32x16_bf16 v[64:79], v[190:193], v[162:165], v[48:63]
	v_add_f32_e32 v2, v118, v2
	v_add_f32_e32 v2, v119, v2
	v_add_f32_e32 v2, v120, v2
	v_add_f32_e32 v2, v121, v2
	v_cvt_pk_bf16_f32 v148, v116, v117
	v_cvt_pk_bf16_f32 v149, v118, v119
	ds_read_b64_tr_b16 v[198:199], v4 offset:25600
	ds_read_b64_tr_b16 v[200:201], v4 offset:26112
	s_waitcnt lgkmcnt(11)
	v_mfma_f32_32x32x16_bf16 v[80:95], v[186:189], v[158:161], v[80:95]
	v_add_f32_e32 v2, v122, v2
	v_add_f32_e32 v2, v123, v2
	v_add_f32_e32 v2, v124, v2
	v_add_f32_e32 v2, v125, v2
	v_cvt_pk_bf16_f32 v142, v120, v121
	v_cvt_pk_bf16_f32 v143, v122, v123
	ds_read_b64_tr_b16 v[116:117], v4 offset:29696
	ds_read_b64_tr_b16 v[118:119], v4 offset:30208
	s_waitcnt lgkmcnt(12)
	v_mfma_f32_32x32x16_bf16 v[64:79], v[182:185], v[158:161], v[64:79]
	v_add_f32_e32 v2, v126, v2
	v_add_f32_e32 v2, v127, v2
	v_add_f32_e32 v2, v96, v2
	v_add_f32_e32 v2, v97, v2
	v_cvt_pk_bf16_f32 v144, v124, v125
	v_cvt_pk_bf16_f32 v145, v126, v127
	ds_read_b64_tr_b16 v[112:113], v4 offset:26624
	ds_read_b64_tr_b16 v[114:115], v4 offset:27136
	s_waitcnt lgkmcnt(13)
	v_mfma_f32_32x32x16_bf16 v[80:95], v[178:181], v[154:157], v[80:95]
	v_add_f32_e32 v2, v98, v2
	v_add_f32_e32 v2, v99, v2
	v_add_f32_e32 v2, v100, v2
	v_add_f32_e32 v2, v101, v2
	v_cvt_pk_bf16_f32 v138, v96, v97
	v_cvt_pk_bf16_f32 v139, v98, v99
	ds_read_b64_tr_b16 v[10:11], v4 offset:30720
	ds_read_b64_tr_b16 v[12:13], v4 offset:31232
	s_waitcnt lgkmcnt(14)
	v_mfma_f32_32x32x16_bf16 v[64:79], v[174:177], v[154:157], v[64:79]
	v_add_f32_e32 v2, v102, v2
	v_add_f32_e32 v2, v103, v2
	v_add_f32_e32 v2, v104, v2
	v_add_f32_e32 v2, v105, v2
	v_cvt_pk_bf16_f32 v140, v100, v101
	v_cvt_pk_bf16_f32 v141, v102, v103
	ds_read_b64_tr_b16 v[6:7], v4 offset:27648
	ds_read_b64_tr_b16 v[8:9], v4 offset:28160
	s_waitcnt lgkmcnt(14)
	v_mfma_f32_32x32x16_bf16 v[80:95], v[170:173], v[150:153], v[80:95]
	v_add_f32_e32 v2, v106, v2
	v_add_f32_e32 v2, v107, v2
	v_add_f32_e32 v2, v108, v2
	v_add_f32_e32 v96, v109, v2
	v_cvt_pk_bf16_f32 v134, v104, v105
	v_cvt_pk_bf16_f32 v135, v106, v107
	ds_read_b64_tr_b16 v[2:3], v4 offset:31744
	ds_read_b64_tr_b16 v[4:5], v4 offset:32256
	v_mfma_f32_32x32x16_bf16 v[64:79], v[166:169], v[150:153], v[64:79]
	v_add_f32_e32 v96, v110, v96
	v_add_f32_e32 v96, v111, v96
	s_nop 0
	v_cvt_pk_bf16_f32 v136, v108, v109
	v_cvt_pk_bf16_f32 v137, v110, v111
	s_cmp_ge_i32 s64, s89
	s_cselect_b64 s[18:19], -1, 0
	s_and_b64 vcc, exec, s[18:19]
	s_cbranch_vccnz .LBB0_1263
	s_add_i32 s13, s31, s90
	s_mov_b32 s20, m0
	s_mov_b32 m0, s13
	s_nop 0
	global_load_lds_dwordx4 v[14:15], off
	s_mov_b32 m0, s20

.LBB0_1267:
	v_add_f32_e32 v237, v237, v96
	v_max_f32_e32 v96, v81, v80
	s_nop 1
	v_max3_f32 v97, v82, v83, v65
	v_max3_f32 v96, v96, v64, v66
	v_max3_f32 v96, v96, v67, v84
	v_max3_f32 v97, v97, v86, v87
	v_max3_f32 v96, v96, v85, v68
	v_max3_f32 v97, v97, v70, v71
	v_max3_f32 v96, v96, v69, v88
	v_max3_f32 v97, v97, v90, v91
	v_max3_f32 v96, v96, v89, v72
	v_max3_f32 v97, v97, v74, v75
	v_max3_f32 v96, v96, v73, v92
	v_max3_f32 v97, v97, v94, v95
	v_max3_f32 v96, v96, v93, v76
	v_max3_f32 v97, v97, v78, v79
	v_max3_f32 v96, v96, v77, v97
	v_mov_b32_e32 v97, v96
	s_nop 1
	v_permlane32_swap_b32_e32 v96, v97
	s_nop 1
	v_max_f32_e32 v96, v96, v97
	v_cmp_lt_f32_e32 vcc, s22, v96
	s_cmp_lg_u64 vcc, 0
	s_cselect_b64 s[20:21], -1, 0
	s_cbranch_vccnz .LBB0_1297

.LBB0_1302:
	v_add_u32_e32 v0, s31, v235
	ds_read_b64_tr_b16 v[6:7], v0 offset:24576
	ds_read_b64_tr_b16 v[8:9], v0 offset:25088
	s_waitcnt lgkmcnt(9)
	v_mfma_f32_32x32x16_bf16 v[96:111], v[194:197], v[162:165], v[48:63]
	v_add_f32_e32 v2, v80, v81
	v_add_f32_e32 v2, v82, v2
	v_add_f32_e32 v2, v83, v2
	v_add_f32_e32 v2, v84, v2
	v_add_f32_e32 v10, v85, v2
	v_cvt_pk_bf16_f32 v146, v80, v81
	v_cvt_pk_bf16_f32 v147, v82, v83
	ds_read_b64_tr_b16 v[2:3], v0 offset:28672
	ds_read_b64_tr_b16 v[4:5], v0 offset:29184
	s_waitcnt lgkmcnt(10)
	v_mfma_f32_32x32x16_bf16 v[48:63], v[190:193], v[162:165], v[48:63]
	v_add_f32_e32 v10, v86, v10
	v_add_f32_e32 v10, v87, v10
	v_add_f32_e32 v10, v88, v10
	v_add_f32_e32 v14, v89, v10
	v_cvt_pk_bf16_f32 v148, v84, v85
	v_cvt_pk_bf16_f32 v149, v86, v87
	ds_read_b64_tr_b16 v[10:11], v0 offset:25600
	ds_read_b64_tr_b16 v[12:13], v0 offset:26112
	s_waitcnt lgkmcnt(11)
	v_mfma_f32_32x32x16_bf16 v[96:111], v[186:189], v[158:161], v[96:111]
	v_add_f32_e32 v14, v90, v14
	v_add_f32_e32 v14, v91, v14
	v_add_f32_e32 v14, v92, v14
	v_add_f32_e32 v14, v93, v14
	v_cvt_pk_bf16_f32 v142, v88, v89
	v_cvt_pk_bf16_f32 v143, v90, v91
	ds_read_b64_tr_b16 v[80:81], v0 offset:29696
	ds_read_b64_tr_b16 v[82:83], v0 offset:30208
	s_waitcnt lgkmcnt(12)
	v_mfma_f32_32x32x16_bf16 v[48:63], v[182:185], v[158:161], v[48:63]
	v_add_f32_e32 v14, v94, v14
	v_add_f32_e32 v14, v95, v14
	v_add_f32_e32 v14, v64, v14
	v_add_f32_e32 v14, v65, v14
	v_cvt_pk_bf16_f32 v144, v92, v93
	v_cvt_pk_bf16_f32 v145, v94, v95
	ds_read_b64_tr_b16 v[84:85], v0 offset:26624
	ds_read_b64_tr_b16 v[86:87], v0 offset:27136
	s_waitcnt lgkmcnt(13)
	v_mfma_f32_32x32x16_bf16 v[96:111], v[178:181], v[154:157], v[96:111]
	v_add_f32_e32 v14, v66, v14
	v_add_f32_e32 v14, v67, v14
	v_add_f32_e32 v14, v68, v14
	v_add_f32_e32 v14, v69, v14
	v_cvt_pk_bf16_f32 v138, v64, v65
	v_cvt_pk_bf16_f32 v139, v66, v67
	ds_read_b64_tr_b16 v[88:89], v0 offset:30720
	ds_read_b64_tr_b16 v[90:91], v0 offset:31232
	s_waitcnt lgkmcnt(14)
	v_mfma_f32_32x32x16_bf16 v[48:63], v[174:177], v[154:157], v[48:63]
	v_add_f32_e32 v14, v70, v14
	v_add_f32_e32 v14, v71, v14
	v_add_f32_e32 v14, v72, v14
	v_add_f32_e32 v14, v73, v14
	v_cvt_pk_bf16_f32 v140, v68, v69
	v_cvt_pk_bf16_f32 v141, v70, v71
	ds_read_b64_tr_b16 v[92:93], v0 offset:27648
	ds_read_b64_tr_b16 v[94:95], v0 offset:28160
	s_waitcnt lgkmcnt(14)
	v_mfma_f32_32x32x16_bf16 v[96:111], v[170:173], v[150:153], v[96:111]
	v_add_f32_e32 v14, v74, v14
	v_add_f32_e32 v14, v75, v14
	v_add_f32_e32 v14, v76, v14
	v_add_f32_e32 v14, v77, v14
	v_cvt_pk_bf16_f32 v134, v72, v73
	v_cvt_pk_bf16_f32 v135, v74, v75
	ds_read_b64_tr_b16 v[112:113], v0 offset:31744
	ds_read_b64_tr_b16 v[114:115], v0 offset:32256
	v_mfma_f32_32x32x16_bf16 v[48:63], v[166:169], v[150:153], v[48:63]
	v_add_f32_e32 v0, v78, v14
	v_add_f32_e32 v0, v79, v0
	s_nop 0
	v_cvt_pk_bf16_f32 v136, v76, v77
	v_cvt_pk_bf16_f32 v137, v78, v79
	s_cmp_lt_i32 s89, 1
	s_cbranch_scc1 .LBB0_1304
	s_lshl_b32 s4, s95, 6
	s_add_i32 s4, s12, s4
	v_or_b32_e32 v14, s83, v226
	s_addk_i32 s4, 0xfec0
	v_add_u32_e32 v14, s10, v14
	v_lshl_or_b32 v15, v227, 2, s4
	v_sub_u32_e32 v14, v15, v14
	v_add_u32_e32 v15, 0xffffff7f, v14
	v_cmp_lt_u32_e32 vcc, s38, v15
	v_add_u32_e32 v15, 0xffffff9f, v14
	s_nop 0
	v_cndmask_b32_e32 v96, v218, v96, vcc
	v_cmp_lt_u32_e32 vcc, s38, v15
	v_add_u32_e32 v15, 0xffffff80, v14
	s_nop 0
	v_cndmask_b32_e32 v48, v218, v48, vcc
	v_cmp_lt_u32_e32 vcc, s38, v15
	v_add_u32_e32 v15, 0xffffffa0, v14
	s_nop 0
	v_cndmask_b32_e32 v97, v218, v97, vcc
	v_cmp_lt_u32_e32 vcc, s38, v15
	v_add_u32_e32 v15, 0xffffff81, v14
	s_nop 0
	v_cndmask_b32_e32 v49, v218, v49, vcc
	v_cmp_lt_u32_e32 vcc, s38, v15
	v_add_u32_e32 v15, 0xffffffa1, v14
	s_nop 0
	v_cndmask_b32_e32 v98, v218, v98, vcc
	v_cmp_lt_u32_e32 vcc, s38, v15
	v_add_u32_e32 v15, 0xffffff82, v14
	s_nop 0
	v_cndmask_b32_e32 v50, v218, v50, vcc
	v_cmp_lt_u32_e32 vcc, s38, v15
	v_add_u32_e32 v15, 0xffffffa2, v14
	s_nop 0
	v_cndmask_b32_e32 v99, v218, v99, vcc
	v_cmp_lt_u32_e32 vcc, s38, v15
	v_add_u32_e32 v15, 0xffffff87, v14
	s_nop 0
	v_cndmask_b32_e32 v51, v218, v51, vcc
	v_cmp_lt_u32_e32 vcc, s38, v15
	v_add_u32_e32 v15, 0xffffffa7, v14
	s_nop 0
	v_cndmask_b32_e32 v100, v218, v100, vcc
	v_cmp_lt_u32_e32 vcc, s38, v15
	v_add_u32_e32 v15, 0xffffff88, v14
	s_nop 0
	v_cndmask_b32_e32 v52, v218, v52, vcc
	v_cmp_lt_u32_e32 vcc, s38, v15
	v_add_u32_e32 v15, 0xffffffa8, v14
	s_nop 0
	v_cndmask_b32_e32 v101, v218, v101, vcc
	v_cmp_lt_u32_e32 vcc, s38, v15
	v_add_u32_e32 v15, 0xffffff89, v14
	s_nop 0
	v_cndmask_b32_e32 v53, v218, v53, vcc
	v_cmp_lt_u32_e32 vcc, s38, v15
	v_add_u32_e32 v15, 0xffffffa9, v14
	s_nop 0
	v_cndmask_b32_e32 v102, v218, v102, vcc
	v_cmp_lt_u32_e32 vcc, s38, v15
	v_add_u32_e32 v15, 0xffffff8a, v14
	s_nop 0
	v_cndmask_b32_e32 v54, v218, v54, vcc
	v_cmp_lt_u32_e32 vcc, s38, v15
	v_add_u32_e32 v15, 0xffffffaa, v14
	s_nop 0
	v_cndmask_b32_e32 v103, v218, v103, vcc
	v_cmp_lt_u32_e32 vcc, s38, v15
	v_add_u32_e32 v15, 0xffffff8f, v14
	s_nop 0
	v_cndmask_b32_e32 v55, v218, v55, vcc
	v_cmp_lt_u32_e32 vcc, s38, v15
	v_add_u32_e32 v15, 0xffffffaf, v14
	s_nop 0
	v_cndmask_b32_e32 v104, v218, v104, vcc
	v_cmp_lt_u32_e32 vcc, s38, v15
	v_add_u32_e32 v15, 0xffffff90, v14
	s_nop 0
	v_cndmask_b32_e32 v56, v218, v56, vcc
	v_cmp_lt_u32_e32 vcc, s38, v15
	v_add_u32_e32 v15, 0xffffffb0, v14
	s_nop 0
	v_cndmask_b32_e32 v105, v218, v105, vcc
	v_cmp_lt_u32_e32 vcc, s38, v15
	v_add_u32_e32 v15, 0xffffff91, v14
	s_nop 0
	v_cndmask_b32_e32 v57, v218, v57, vcc
	v_cmp_lt_u32_e32 vcc, s38, v15
	v_add_u32_e32 v15, 0xffffffb1, v14
	s_nop 0
	v_cndmask_b32_e32 v106, v218, v106, vcc
	v_cmp_lt_u32_e32 vcc, s38, v15
	v_add_u32_e32 v15, 0xffffff92, v14
	s_nop 0
	v_cndmask_b32_e32 v58, v218, v58, vcc
	v_cmp_lt_u32_e32 vcc, s38, v15
	v_add_u32_e32 v15, 0xffffffb2, v14
	s_nop 0
	v_cndmask_b32_e32 v107, v218, v107, vcc
	v_cmp_lt_u32_e32 vcc, s38, v15
	v_add_u32_e32 v15, 0xffffff97, v14
	s_nop 0
	v_cndmask_b32_e32 v59, v218, v59, vcc
	v_cmp_lt_u32_e32 vcc, s38, v15
	v_add_u32_e32 v15, 0xffffffb7, v14
	s_nop 0
	v_cndmask_b32_e32 v108, v218, v108, vcc
	v_cmp_lt_u32_e32 vcc, s38, v15
	v_add_u32_e32 v15, 0xffffff98, v14
	s_nop 0
	v_cndmask_b32_e32 v60, v218, v60, vcc
	v_cmp_lt_u32_e32 vcc, s38, v15
	v_add_u32_e32 v15, 0xffffffb8, v14
	s_nop 0
	v_cndmask_b32_e32 v109, v218, v109, vcc
	v_cmp_lt_u32_e32 vcc, s38, v15
	v_add_u32_e32 v15, 0xffffff99, v14
	s_nop 0
	v_cndmask_b32_e32 v61, v218, v61, vcc
	v_cmp_lt_u32_e32 vcc, s38, v15
	v_add_u32_e32 v15, 0xffffffb9, v14
	s_nop 0
	v_cndmask_b32_e32 v110, v218, v110, vcc
	v_cmp_lt_u32_e32 vcc, s38, v15
	v_add_u32_e32 v15, 0xffffff9a, v14
	v_add_u32_e32 v14, 0xffffffba, v14
	v_cndmask_b32_e32 v62, v218, v62, vcc
	v_cmp_lt_u32_e32 vcc, s38, v15
	s_nop 1
	v_cndmask_b32_e32 v111, v218, v111, vcc
	v_cmp_lt_u32_e32 vcc, s38, v14
	s_nop 1
	v_cndmask_b32_e32 v63, v218, v63, vcc
.LBB0_1304:
	v_max_f32_e32 v14, v97, v96
	s_nop 3
	v_max3_f32 v15, v98, v99, v49
	v_max3_f32 v14, v14, v48, v50
	v_max3_f32 v14, v14, v51, v100
	v_max3_f32 v15, v15, v102, v103
	v_max3_f32 v14, v14, v101, v52
	v_max3_f32 v15, v15, v54, v55
	v_max3_f32 v14, v14, v53, v104
	v_max3_f32 v15, v15, v106, v107
	v_max3_f32 v14, v14, v105, v56
	v_max3_f32 v15, v15, v58, v59
	v_max3_f32 v14, v14, v57, v108
	v_max3_f32 v15, v15, v110, v111
	v_max3_f32 v14, v14, v109, v60
	v_max3_f32 v15, v15, v62, v63
	v_max3_f32 v14, v14, v61, v15
	v_mov_b32_e32 v15, v14
	s_nop 1
	v_permlane32_swap_b32_e32 v14, v15
	s_nop 1
	v_max_f32_e32 v14, v14, v15
	v_cmp_lt_f32_e32 vcc, s22, v14
	s_cmp_lg_u64 vcc, 0
	s_mov_b32 s94, 0x40000
	s_mov_b32 s95, 0x20000
	v_add_f32_e32 v0, v237, v0
	s_cselect_b64 s[4:5], -1, 0
	s_cbranch_vccnz .LBB0_1395
